# GEMM epilogues: result stores as global_store (no lgkmcnt coupling with the next unit's LDS waits)
# speedup vs baseline: 1.0176x; 1.0039x over previous
;     DI void operator()(const f32x4 (&acc)[2][2][4][2], const Unit& u, int wr, int wc, int fr, int fq, LAS unsigned char* lds) const {
;     ...
;             {
;                 float* EGb = edge + (size_t)u.pm * 4 * UPN + u.pn * 256;
;                 if (wr == 0 && fr < 2) {
; #pragma unroll
;                     for (int bj = 0; bj < 2; ++bj)
; #pragma unroll
;                         for (int n = 0; n < 2; ++n) *(f32x4*)(EGb + (unsigned)(fr * UPN + cl + bj * 128 + 4 * n)) = acc[0][bj][0][n];
;                 }
;                 if (wr == 1 && fr >= 14) {
; #pragma unroll
;                     for (int bj = 0; bj < 2; ++bj)
; #pragma unroll
;                         for (int n = 0; n < 2; ++n) *(f32x4*)(EGb + (unsigned)((fr - 12) * UPN + cl + bj * 128 + 4 * n)) = acc[1][bj][3][n];
;                 }
;             }
.LBB0_259:
	s_or_b64 exec, exec, s[20:21]
	s_mul_i32 s21, s10, 0x16000
	s_mul_hi_i32 s20, s10, 0x16000
	s_add_u32 s37, s18, s21
	s_addc_u32 s50, s19, s20
	s_ashr_i32 s49, s48, 31
	s_lshl_b64 s[20:21], s[48:49], 2
	s_add_u32 s20, s37, s20
	s_addc_u32 s21, s50, s21
	s_add_u32 s50, s20, 0x16be2000
	s_addc_u32 s51, s21, 0
	s_cmp_eq_u32 s61, 0
	s_cselect_b64 s[56:57], -1, 0
	s_cmp_lg_u32 s61, 0
	v_cmp_gt_u32_e32 vcc, 2, v130
	s_movk_i32 s20, 0x1600
	s_cselect_b64 s[76:77], -1, 0
	s_and_b64 s[52:53], s[56:57], vcc
	v_mad_u32_u24 v0, v130, s20, v146
	s_and_saveexec_b64 s[20:21], s[52:53]
	s_cbranch_execz .LBB0_261
	v_lshl_add_u64 v[132:133], v[0:1], 2, s[50:51]
	global_store_dwordx4 v[132:133], v[126:129], off
	global_store_dwordx4 v[132:133], v[122:125], off offset:16
	v_add_u32_e32 v132, 0x80, v0
	v_mov_b32_e32 v133, v1
	v_lshl_add_u64 v[132:133], v[132:133], 2, s[50:51]
	global_store_dwordx4 v[132:133], v[110:113], off
	v_add_u32_e32 v132, 0x84, v0
	v_mov_b32_e32 v133, v1
	v_lshl_add_u64 v[132:133], v[132:133], 2, s[50:51]
	global_store_dwordx4 v[132:133], v[102:105], off
.LBB0_261:
	s_or_b64 exec, exec, s[20:21]
	s_cmp_eq_u32 s61, 1
	s_cselect_b64 s[54:55], -1, 0
	s_cmp_lg_u32 s61, 1
	v_cmp_lt_u32_e32 vcc, 13, v130
	s_cselect_b64 s[52:53], -1, 0
	s_and_b64 vcc, s[54:55], vcc
	s_and_saveexec_b64 s[20:21], vcc
	s_cbranch_execz .LBB0_263
	v_add_u32_e32 v132, 0xfffef800, v0
	v_mov_b32_e32 v133, v1
	v_lshl_add_u64 v[132:133], v[132:133], 2, s[50:51]
	global_store_dwordx4 v[132:133], v[30:33], off
	global_store_dwordx4 v[132:133], v[22:25], off offset:16
	v_add_u32_e32 v132, 0xfffef880, v0
	v_mov_b32_e32 v133, v1
	v_lshl_add_u64 v[132:133], v[132:133], 2, s[50:51]
	v_add_u32_e32 v0, 0xfffef884, v0
	global_store_dwordx4 v[132:133], v[6:9], off
	v_lshl_add_u64 v[132:133], v[0:1], 2, s[50:51]
	global_store_dwordx4 v[132:133], v[2:5], off

;     DI void operator()(const f32x4 (&acc)[2][2][4][2], const Unit& u, int wr, int wc, int fr, int fq, LAS unsigned char* lds) const {
;     ...
;                 for (int n = 0; n < 2; ++n) {
;                     float o[4][4];
; #pragma unroll
;                     for (int e = 0; e < 4; ++e) {
;                         const LAS float* cwp = CWL + cl + 4 * n + e;
;                         const float xpa = hasp ? xp[4 * n + e] : 0.f, xpg = hasp ? xp[128 + 4 * n + e] : 0.f;
;                         const float xna = hasn ? xn[4 * n + e] : 0.f, xng = hasn ? xn[128 + 4 * n + e] : 0.f;
;                         float ap[4], gp[4], an[4], gn[4];
; #pragma unroll
;                         for (int m = 0; m < 4; ++m) {
;                             const float ca = acc[ai][0][m][n][e], cg2 = acc[ai][1][m][n][e];
;                             const float oa_p = (fr == 15) ? acc[ai][0][m == 0 ? 0 : m - 1][n][e] : ca, og_p = (fr == 15) ? acc[ai][1][m == 0 ? 0 : m - 1][n][e] : cg2;
;                             const float oa_n = (fr == 0) ? acc[ai][0][m == 3 ? 3 : m + 1][n][e] : ca, og_n = (fr == 0) ? acc[ai][1][m == 3 ? 3 : m + 1][n][e] : cg2;
;                             ap[m] = __int_as_float(__builtin_amdgcn_mov_dpp(__float_as_int(oa_p), 0x121, 0xF, 0xF, false));
;                             gp[m] = __int_as_float(__builtin_amdgcn_mov_dpp(__float_as_int(og_p), 0x121, 0xF, 0xF, false));
;                             an[m] = __int_as_float(__builtin_amdgcn_mov_dpp(__float_as_int(oa_n), 0x12F, 0xF, 0xF, false));
;                             gn[m] = __int_as_float(__builtin_amdgcn_mov_dpp(__float_as_int(og_n), 0x12F, 0xF, 0xF, false));
;                         }
;                         ap[0] = (fr == 0) ? xpa : ap[0]; gp[0] = (fr == 0) ? xpg : gp[0];
;                         an[3] = (fr == 15) ? xna : an[3]; gn[3] = (fr == 15) ? xng : gn[3];
;                         const float w0a = cwp[0], w1a = cwp[128], w2a = cwp[256], bba = cwp[384];
;                         const float w0g = cwp[512], w1g = cwp[640], w2g = cwp[768], bbg = cwp[896];
; #pragma unroll
;                         for (int m = 0; m < 4; ++m) {
;                             const float av = w0a * ap[m] + w1a * acc[ai][0][m][n][e] + w2a * an[m] + bba;
;                             const float gv = w0g * gp[m] + w1g * acc[ai][1][m][n][e] + w2g * gn[m] + bbg;
.LBB0_279:
	s_waitcnt lgkmcnt(5)
	v_cndmask_b32_e64 v240, v245, v240, s[44:45]
	s_waitcnt lgkmcnt(4)
	v_cndmask_b32_e64 v173, v180, v173, s[42:43]
	s_waitcnt lgkmcnt(1)
	v_mul_f32_e32 v180, v112, v171
	v_fmac_f32_e32 v180, v240, v170
	s_waitcnt lgkmcnt(0)
	v_fmac_f32_e32 v180, v168, v243
	v_add_f32_e32 v180, v169, v180
	v_mul_f32_e32 v240, 0xbfb8aa3b, v180
	v_exp_f32_e32 v240, v240
	v_cndmask_b32_e64 v241, v244, v241, s[44:45]
	v_cndmask_b32_e64 v172, v179, v172, s[42:43]
	v_mul_f32_e32 v179, v128, v165
	v_add_f32_e32 v240, 1.0, v240
	v_rcp_f32_e32 v240, v240
	v_fmac_f32_e32 v179, v241, v164
	v_fmac_f32_e32 v179, v166, v242
	v_mul_f32_e32 v241, v96, v171
	v_add_f32_e32 v179, v167, v179
	v_fmac_f32_e32 v241, v170, v238
	v_mul_f32_e32 v180, v180, v240
	v_fmac_f32_e32 v241, v168, v239
	v_mul_f32_e32 v179, v179, v180
	v_mul_f32_e32 v180, v120, v165
	v_add_f32_e32 v238, v169, v241
	v_fmac_f32_e32 v180, v164, v236
	v_mul_f32_e32 v239, 0xbfb8aa3b, v238
	v_fmac_f32_e32 v180, v166, v237
	v_mul_f32_e32 v237, v80, v171
	v_mul_f32_e32 v171, v72, v171
	v_exp_f32_e32 v239, v239
	v_fmac_f32_e32 v171, v170, v233
	v_fmac_f32_e32 v237, v170, v234
	v_fmac_f32_e32 v171, v173, v168
	v_fmac_f32_e32 v237, v168, v235
	v_add_f32_e32 v168, v169, v171
	v_add_f32_e32 v234, v169, v237
	v_mul_f32_e32 v169, 0xbfb8aa3b, v168
	v_add_f32_e32 v239, 1.0, v239
	v_exp_f32_e32 v169, v169
	v_rcp_f32_e32 v239, v239
	v_add_f32_e32 v180, v167, v180
	v_cndmask_b32_e64 v163, v229, v163, s[42:43]
	v_add_f32_e32 v169, 1.0, v169
	v_mul_f32_e32 v236, v238, v239
	v_rcp_f32_e32 v169, v169
	v_mul_f32_e32 v180, v180, v236
	v_mul_f32_e32 v236, v108, v165
	v_mul_f32_e32 v165, v92, v165
	v_fmac_f32_e32 v165, v164, v230
	v_fmac_f32_e32 v236, v164, v231
	v_fmac_f32_e32 v165, v172, v166
	v_fmac_f32_e32 v236, v166, v232
	v_add_f32_e32 v164, v167, v165
	v_mul_f32_e32 v165, v168, v169
	v_add_f32_e32 v231, v167, v236
	v_mul_f32_e32 v171, v164, v165
	v_cndmask_b32_e64 v164, v227, v222, s[44:45]
	v_mul_f32_e32 v167, v111, v161
	v_fmac_f32_e32 v167, v164, v160
	v_fmac_f32_e32 v167, v158, v225
	v_add_f32_e32 v164, v159, v167
	v_mul_f32_e32 v167, 0xbfb8aa3b, v164
	v_exp_f32_e32 v167, v167
	v_cndmask_b32_e64 v165, v226, v223, s[44:45]
	v_mul_f32_e32 v166, v127, v155
	v_fmac_f32_e32 v166, v165, v154
	v_fmac_f32_e32 v166, v156, v224
	v_add_f32_e32 v165, v157, v166
	v_add_f32_e32 v166, 1.0, v167
	v_mul_f32_e32 v167, v95, v161
	v_fmac_f32_e32 v167, v160, v220
	v_fmac_f32_e32 v167, v158, v221
	v_add_f32_e32 v167, v159, v167
	v_rcp_f32_e32 v166, v166
	v_mul_f32_e32 v168, 0xbfb8aa3b, v167
	v_exp_f32_e32 v168, v168
	v_cndmask_b32_e64 v162, v228, v162, s[42:43]
	v_mul_f32_e32 v164, v164, v166
	v_mul_f32_e32 v172, v165, v164
	v_add_f32_e32 v165, 1.0, v168
	v_rcp_f32_e32 v165, v165
	v_mul_f32_e32 v164, v119, v155
	v_fmac_f32_e32 v164, v154, v218
	v_fmac_f32_e32 v164, v156, v219
	v_add_f32_e32 v164, v157, v164
	v_mul_f32_e32 v165, v167, v165
	v_mul_f32_e32 v173, v164, v165
	v_mul_f32_e32 v165, v79, v161
	v_mul_f32_e32 v161, v71, v161
	v_fmac_f32_e32 v161, v160, v215
	v_fmac_f32_e32 v165, v160, v216
	v_fmac_f32_e32 v161, v163, v158
	v_fmac_f32_e32 v165, v158, v217
	v_add_f32_e32 v158, v159, v161
	v_add_f32_e32 v165, v159, v165
	v_mul_f32_e32 v159, 0xbfb8aa3b, v158
	v_exp_f32_e32 v159, v159
	v_mul_f32_e32 v164, v107, v155
	v_mul_f32_e32 v155, v91, v155
	v_fmac_f32_e32 v155, v154, v212
	v_add_f32_e32 v159, 1.0, v159
	v_rcp_f32_e32 v159, v159
	v_fmac_f32_e32 v164, v154, v213
	v_fmac_f32_e32 v155, v162, v156
	v_fmac_f32_e32 v164, v156, v214
	v_add_f32_e32 v154, v157, v155
	v_mul_f32_e32 v155, v158, v159
	v_add_f32_e32 v164, v157, v164
	v_mul_f32_e32 v212, v154, v155
	v_cndmask_b32_e64 v154, v207, v195, s[44:45]
	v_mul_f32_e32 v157, v110, v151
	v_fmac_f32_e32 v157, v154, v150
	v_fmac_f32_e32 v157, v148, v205
	v_add_f32_e32 v154, v149, v157
	v_mul_f32_e32 v157, 0xbfb8aa3b, v154
	v_exp_f32_e32 v157, v157
	v_cndmask_b32_e64 v155, v206, v201, s[44:45]
	v_mul_f32_e32 v156, v126, v133
	v_fmac_f32_e32 v156, v155, v132
	v_fmac_f32_e32 v156, v130, v204
	v_add_f32_e32 v155, v131, v156
	v_add_f32_e32 v156, 1.0, v157
	v_mul_f32_e32 v157, v94, v151
	v_fmac_f32_e32 v157, v150, v202
	v_fmac_f32_e32 v157, v148, v203
	v_add_f32_e32 v157, v149, v157
	v_rcp_f32_e32 v156, v156
	v_mul_f32_e32 v158, 0xbfb8aa3b, v157
	v_exp_f32_e32 v158, v158
	v_cndmask_b32_e64 v153, v211, v153, s[42:43]
	v_mul_f32_e32 v154, v154, v156
	v_mul_f32_e32 v195, v155, v154
	v_add_f32_e32 v155, 1.0, v158
	v_rcp_f32_e32 v155, v155
	v_mul_f32_e32 v154, v118, v133
	v_fmac_f32_e32 v154, v132, v199
	v_fmac_f32_e32 v154, v130, v200
	v_add_f32_e32 v154, v131, v154
	v_mul_f32_e32 v155, v157, v155
	v_mul_f32_e32 v199, v154, v155
	v_mul_f32_e32 v155, v78, v151
	v_mul_f32_e32 v151, v70, v151
	v_fmac_f32_e32 v155, v150, v196
	v_fmac_f32_e32 v151, v150, v193
	v_fmac_f32_e32 v155, v148, v198
	v_fmac_f32_e32 v151, v153, v148
	v_add_f32_e32 v155, v149, v155
	v_add_f32_e32 v148, v149, v151
	v_mul_f32_e32 v166, 0xbfb8aa3b, v165
	v_mul_f32_e32 v156, 0xbfb8aa3b, v155
	v_mul_f32_e32 v149, 0xbfb8aa3b, v148
	v_exp_f32_e32 v166, v166
	v_exp_f32_e32 v156, v156
	v_exp_f32_e32 v149, v149
	v_mul_f32_e32 v154, v106, v133
	v_add_f32_e32 v166, 1.0, v166
	v_add_f32_e32 v156, 1.0, v156
	v_add_f32_e32 v149, 1.0, v149
	v_rcp_f32_e32 v166, v166
	v_rcp_f32_e32 v156, v156
	v_rcp_f32_e32 v149, v149
	v_mul_f32_e32 v133, v90, v133
	v_cndmask_b32_e64 v152, v210, v152, s[42:43]
	v_fmac_f32_e32 v133, v132, v0
	v_fmac_f32_e32 v154, v132, v190
	v_fmac_f32_e32 v133, v152, v130
	v_mul_f32_e32 v160, v165, v166
	v_fmac_f32_e32 v154, v130, v194
	v_mul_f32_e32 v150, v155, v156
	v_add_f32_e32 v0, v131, v133
	v_mul_f32_e32 v130, v148, v149
	ds_read2_b32 v[156:157], v189 offset0:3 offset1:131
	v_add_u32_e32 v193, 12, v189
	v_mul_f32_e32 v213, v164, v160
	v_add_f32_e32 v154, v131, v154
	v_mul_f32_e32 v196, v0, v130
	ds_read2_b32 v[130:131], v191 offset0:3 offset1:131
	ds_read2st64_b32 v[158:159], v193 offset0:4 offset1:6
	ds_read2st64_b32 v[160:161], v193 offset0:8 offset1:10
	ds_read2st64_b32 v[162:163], v193 offset0:12 offset1:14
	v_mov_b32_dpp v164, v129 row_ror:1 row_mask:0xf bank_mask:0xf
	v_mov_b32_dpp v165, v113 row_ror:1 row_mask:0xf bank_mask:0xf
	v_mov_b32_e32 v168, v129
	s_waitcnt lgkmcnt(1)
;     DI void operator()(const f32x4 (&acc)[2][2][4][2], const Unit& u, int wr, int wc, int fr, int fq, LAS unsigned char* lds) const {
;     ...
;                         for (int m = 0; m < 4; ++m) {
;                             const float ca = acc[ai][0][m][n][e], cg2 = acc[ai][1][m][n][e];
;                             const float oa_p = (fr == 15) ? acc[ai][0][m == 0 ? 0 : m - 1][n][e] : ca, og_p = (fr == 15) ? acc[ai][1][m == 0 ? 0 : m - 1][n][e] : cg2;
;                             const float oa_n = (fr == 0) ? acc[ai][0][m == 3 ? 3 : m + 1][n][e] : ca, og_n = (fr == 0) ? acc[ai][1][m == 3 ? 3 : m + 1][n][e] : cg2;
;                             ap[m] = __int_as_float(__builtin_amdgcn_mov_dpp(__float_as_int(oa_p), 0x121, 0xF, 0xF, false));
;                             gp[m] = __int_as_float(__builtin_amdgcn_mov_dpp(__float_as_int(og_p), 0x121, 0xF, 0xF, false));
;                             an[m] = __int_as_float(__builtin_amdgcn_mov_dpp(__float_as_int(oa_n), 0x12F, 0xF, 0xF, false));
;                             gn[m] = __int_as_float(__builtin_amdgcn_mov_dpp(__float_as_int(og_n), 0x12F, 0xF, 0xF, false));
;                         }
;                         ap[0] = (fr == 0) ? xpa : ap[0]; gp[0] = (fr == 0) ? xpg : gp[0];
;                         an[3] = (fr == 15) ? xna : an[3]; gn[3] = (fr == 15) ? xng : gn[3];
;                         const float w0a = cwp[0], w1a = cwp[128], w2a = cwp[256], bba = cwp[384];
;                         const float w0g = cwp[512], w1g = cwp[640], w2g = cwp[768], bbg = cwp[896];
; #pragma unroll
;                         for (int m = 0; m < 4; ++m) {
;                             const float av = w0a * ap[m] + w1a * acc[ai][0][m][n][e] + w2a * an[m] + bba;
;                             const float gv = w0g * gp[m] + w1g * acc[ai][1][m][n][e] + w2g * gn[m] + bbg;
;                             o[m][e] = av * siluf_(gv);
;                         }
;                         __builtin_amdgcn_sched_barrier(0);
;                     }
; #pragma unroll
;                     for (int m = 0; m < 4; ++m) {
;                         u32x2 ov; ov[0] = pk_bf16(o[m][0], o[m][1]); ov[1] = pk_bf16(o[m][2], o[m][3]);
;                         *(u32x2*)(ACTb + (unsigned)((wr * 64 + fr + ai * HALF + m * 16) * DFF + cl + 4 * n)) = ov;
;                     }
	v_mov_b32_e32 v167, v160
	v_mov_b32_e32 v169, v113
	v_mov_b32_e32 v160, v157
	v_cndmask_b32_e64 v0, v129, v121, s[44:45]
	v_cndmask_b32_e64 v133, v113, v97, s[44:45]
	v_cndmask_b32_e64 v165, v165, v208, s[44:45]
	v_cndmask_b32_e64 v164, v164, v209, s[44:45]
	v_mov_b32_e32 v166, v156
	v_pk_mul_f32 v[156:157], v[168:169], v[160:161]
	v_mov_b32_dpp v132, v0 row_ror:15 row_mask:0xf bank_mask:0xf
	v_mov_b32_dpp v133, v133 row_ror:15 row_mask:0xf bank_mask:0xf
	v_pk_fma_f32 v[156:157], v[164:165], v[166:167], v[156:157]
	v_mov_b32_e32 v164, v158
	s_waitcnt lgkmcnt(0)
	v_mov_b32_e32 v165, v162
	v_pk_fma_f32 v[132:133], v[164:165], v[132:133], v[156:157]
	v_mov_b32_e32 v162, v159
	v_pk_add_f32 v[132:133], v[162:163], v[132:133]
	v_cndmask_b32_e64 v0, v121, v129, s[42:43]
	v_mul_f32_e32 v156, 0xbfb8aa3b, v133
	v_exp_f32_e32 v158, v156
	v_cndmask_b32_e64 v149, v97, v113, s[42:43]
	v_mov_b32_e32 v159, v97
	v_mul_f32_e32 v194, v154, v150
	v_add_f32_e32 v158, 1.0, v158
	v_rcp_f32_e32 v168, v158
	v_mov_b32_e32 v158, v121
	v_cndmask_b32_e64 v150, v121, v109, s[44:45]
	v_cndmask_b32_e64 v151, v97, v81, s[44:45]
	v_mov_b32_dpp v148, v0 row_ror:1 row_mask:0xf bank_mask:0xf
	v_mov_b32_dpp v149, v149 row_ror:1 row_mask:0xf bank_mask:0xf
	v_pk_mul_f32 v[158:159], v[158:159], v[160:161]
	v_mov_b32_dpp v150, v150 row_ror:15 row_mask:0xf bank_mask:0xf
	v_mov_b32_dpp v151, v151 row_ror:15 row_mask:0xf bank_mask:0xf
	v_pk_fma_f32 v[148:149], v[166:167], v[148:149], v[158:159]
	v_mul_f32_e32 v133, v133, v168
	v_pk_fma_f32 v[148:149], v[164:165], v[150:151], v[148:149]
	v_mul_f32_e32 v158, v132, v133
	v_pk_add_f32 v[148:149], v[162:163], v[148:149]
	v_cndmask_b32_e64 v0, v109, v121, s[42:43]
	v_mul_f32_e32 v150, 0xbfb8aa3b, v149
	v_exp_f32_e32 v150, v150
	v_cndmask_b32_e64 v153, v81, v97, s[42:43]
	v_mov_b32_e32 v133, v81
	v_cndmask_b32_e64 v154, v109, v93, s[44:45]
	v_add_f32_e32 v132, 1.0, v150
	v_rcp_f32_e32 v159, v132
	v_mov_b32_e32 v132, v109
	v_cndmask_b32_e64 v155, v81, v73, s[44:45]
	v_mov_b32_dpp v152, v0 row_ror:1 row_mask:0xf bank_mask:0xf
	v_mov_b32_dpp v153, v153 row_ror:1 row_mask:0xf bank_mask:0xf
	v_pk_mul_f32 v[132:133], v[132:133], v[160:161]
	v_mov_b32_dpp v154, v154 row_ror:15 row_mask:0xf bank_mask:0xf
	v_mov_b32_dpp v155, v155 row_ror:15 row_mask:0xf bank_mask:0xf
	v_pk_fma_f32 v[132:133], v[166:167], v[152:153], v[132:133]
	v_mov_b32_dpp v151, v73 row_ror:15 row_mask:0xf bank_mask:0xf
	v_pk_fma_f32 v[132:133], v[164:165], v[154:155], v[132:133]
	v_cndmask_b32_e64 v0, v93, v109, s[42:43]
	v_pk_add_f32 v[132:133], v[162:163], v[132:133]
	v_cndmask_b32_e64 v190, v73, v81, s[42:43]
	v_mul_f32_e32 v150, 0xbfb8aa3b, v133
	v_exp_f32_e32 v152, v150
	v_cndmask_b32_e64 v131, v151, v131, s[42:43]
	v_mov_b32_e32 v150, v93
	v_mov_b32_e32 v151, v73
	v_mov_b32_dpp v156, v0 row_ror:1 row_mask:0xf bank_mask:0xf
	v_mov_b32_dpp v157, v190 row_ror:1 row_mask:0xf bank_mask:0xf
	v_mov_b32_dpp v0, v93 row_ror:15 row_mask:0xf bank_mask:0xf
	v_pk_mul_f32 v[150:151], v[150:151], v[160:161]
	v_cndmask_b32_e64 v130, v0, v130, s[42:43]
	v_pk_fma_f32 v[150:151], v[166:167], v[156:157], v[150:151]
	v_mul_f32_e32 v235, 0xbfb8aa3b, v234
	v_pk_fma_f32 v[130:131], v[130:131], v[164:165], v[150:151]
	v_exp_f32_e32 v235, v235
	v_pk_add_f32 v[130:131], v[162:163], v[130:131]
	s_mul_i32 s21, s10, 0x160000
	v_mul_f32_e32 v0, 0xbfb8aa3b, v131
	v_exp_f32_e32 v0, v0
	v_add_f32_e32 v232, 1.0, v235
	v_add_f32_e32 v150, 1.0, v152
	v_rcp_f32_e32 v232, v232
	v_add_f32_e32 v0, 1.0, v0
	s_mul_hi_i32 s20, s10, 0x160000
	s_add_u32 s37, s16, s21
	v_rcp_f32_e32 v150, v150
	v_rcp_f32_e32 v0, v0
	s_addc_u32 s49, s17, s20
	s_ashr_i32 s51, s50, 31
	s_lshl_b64 s[20:21], s[50:51], 1
	s_add_u32 s50, s37, s20
	v_mul_f32_e32 v170, v234, v232
	s_addc_u32 s51, s49, s21
	v_mul_f32_e32 v149, v149, v159
	v_mul_f32_e32 v133, v133, v150
	v_mul_f32_e32 v0, v131, v0
	v_mul_f32_e32 v170, v231, v170
	v_mul_f32_e32 v148, v148, v149
	v_mul_f32_e32 v149, v132, v133
	v_mul_f32_e32 v150, v130, v0
	s_movk_i32 s20, 0xb00
	v_mul_lo_u32 v190, v187, s20
	v_add_u32_e32 v0, v146, v190
	v_cvt_pk_bf16_f32 v130, v195, v172
	v_lshl_add_u64 v[132:133], v[0:1], 1, s[50:51]
	v_add_u32_e32 v198, 0xb000, v190
	v_cvt_pk_bf16_f32 v131, v179, v158
	global_store_dwordx2 v[132:133], v[130:131], off
	v_cvt_pk_bf16_f32 v130, v199, v173
	v_add_u32_e32 v0, v198, v146
	v_add_u32_e32 v199, 0x16000, v190
	v_lshl_add_u64 v[132:133], v[0:1], 1, s[50:51]
	v_add_u32_e32 v0, v199, v146
	v_add_u32_e32 v200, 0x21000, v190
	v_cvt_pk_bf16_f32 v131, v180, v148
	global_store_dwordx2 v[132:133], v[130:131], off
	v_lshl_add_u64 v[132:133], v[0:1], 1, s[50:51]
	v_add_u32_e32 v0, v200, v146
	v_cvt_pk_bf16_f32 v130, v194, v213
	v_cvt_pk_bf16_f32 v131, v170, v149
	global_store_dwordx2 v[132:133], v[130:131], off
	v_lshl_add_u64 v[132:133], v[0:1], 1, s[50:51]
	v_cvt_pk_bf16_f32 v130, v196, v212
	v_cvt_pk_bf16_f32 v131, v171, v150
	global_store_dwordx2 v[132:133], v[130:131], off
	v_mov_b32_e32 v210, 0
	s_and_b64 vcc, exec, s[46:47]
	v_mov_b32_e32 v211, 0
	s_cbranch_vccnz .LBB0_281
	ds_read_b32 v211, v197 offset:16

;     DI void operator()(const f32x4 (&acc)[2][2][4][2], const Unit& u, int wr, int wc, int fr, int fq, LAS unsigned char* lds) const {
;     ...
;                 for (int n = 0; n < 2; ++n) {
;                     float o[4][4];
; #pragma unroll
;                     for (int e = 0; e < 4; ++e) {
;                         const LAS float* cwp = CWL + cl + 4 * n + e;
;                         const float xpa = hasp ? xp[4 * n + e] : 0.f, xpg = hasp ? xp[128 + 4 * n + e] : 0.f;
;                         const float xna = hasn ? xn[4 * n + e] : 0.f, xng = hasn ? xn[128 + 4 * n + e] : 0.f;
;                         float ap[4], gp[4], an[4], gn[4];
; #pragma unroll
;                         for (int m = 0; m < 4; ++m) {
;                             const float ca = acc[ai][0][m][n][e], cg2 = acc[ai][1][m][n][e];
;                             const float oa_p = (fr == 15) ? acc[ai][0][m == 0 ? 0 : m - 1][n][e] : ca, og_p = (fr == 15) ? acc[ai][1][m == 0 ? 0 : m - 1][n][e] : cg2;
;                             const float oa_n = (fr == 0) ? acc[ai][0][m == 3 ? 3 : m + 1][n][e] : ca, og_n = (fr == 0) ? acc[ai][1][m == 3 ? 3 : m + 1][n][e] : cg2;
;                             ap[m] = __int_as_float(__builtin_amdgcn_mov_dpp(__float_as_int(oa_p), 0x121, 0xF, 0xF, false));
;                             gp[m] = __int_as_float(__builtin_amdgcn_mov_dpp(__float_as_int(og_p), 0x121, 0xF, 0xF, false));
;                             an[m] = __int_as_float(__builtin_amdgcn_mov_dpp(__float_as_int(oa_n), 0x12F, 0xF, 0xF, false));
;                             gn[m] = __int_as_float(__builtin_amdgcn_mov_dpp(__float_as_int(og_n), 0x12F, 0xF, 0xF, false));
;                         }
;                         ap[0] = (fr == 0) ? xpa : ap[0]; gp[0] = (fr == 0) ? xpg : gp[0];
;                         an[3] = (fr == 15) ? xna : an[3]; gn[3] = (fr == 15) ? xng : gn[3];
;                         const float w0a = cwp[0], w1a = cwp[128], w2a = cwp[256], bba = cwp[384];
;                         const float w0g = cwp[512], w1g = cwp[640], w2g = cwp[768], bbg = cwp[896];
; #pragma unroll
;                         for (int m = 0; m < 4; ++m) {
;                             const float av = w0a * ap[m] + w1a * acc[ai][0][m][n][e] + w2a * an[m] + bba;
;                             const float gv = w0g * gp[m] + w1g * acc[ai][1][m][n][e] + w2g * gn[m] + bbg;
.LBB0_295:
	s_waitcnt lgkmcnt(0)
	v_cndmask_b32_e64 v197, v253, v248, s[44:45]
	v_cndmask_b32_e64 v173, v180, v173, s[42:43]
	v_mul_f32_e32 v180, v104, v171
	v_fmac_f32_e32 v180, v197, v170
	v_fmac_f32_e32 v180, v168, v251
	v_add_f32_e32 v180, v169, v180
	v_mul_f32_e32 v197, 0xbfb8aa3b, v180
	v_exp_f32_e32 v197, v197
	v_cndmask_b32_e64 v248, v252, v249, s[44:45]
	v_cndmask_b32_e64 v172, v179, v172, s[42:43]
	v_mul_f32_e32 v179, v124, v165
	v_add_f32_e32 v197, 1.0, v197
	v_rcp_f32_e32 v197, v197
	v_fmac_f32_e32 v179, v248, v164
	v_mul_f32_e32 v248, v88, v171
	v_fmac_f32_e32 v179, v166, v250
	v_fmac_f32_e32 v248, v170, v246
	v_add_f32_e32 v179, v167, v179
	v_fmac_f32_e32 v248, v168, v247
	v_mul_f32_e32 v180, v180, v197
	v_add_f32_e32 v246, v169, v248
	v_mul_f32_e32 v179, v179, v180
	v_mul_f32_e32 v180, v116, v165
	v_mul_f32_e32 v247, 0xbfb8aa3b, v246
	v_fmac_f32_e32 v180, v164, v244
	v_mul_f32_e32 v244, v76, v171
	v_mul_f32_e32 v171, v68, v171
	v_exp_f32_e32 v247, v247
	v_fmac_f32_e32 v171, v170, v241
	v_fmac_f32_e32 v244, v170, v242
	v_fmac_f32_e32 v171, v173, v168
	v_fmac_f32_e32 v244, v168, v243
	v_add_f32_e32 v168, v169, v171
	v_add_f32_e32 v242, v169, v244
	v_mul_f32_e32 v169, 0xbfb8aa3b, v168
	v_add_f32_e32 v197, 1.0, v247
	v_exp_f32_e32 v169, v169
	v_rcp_f32_e32 v197, v197
	v_fmac_f32_e32 v180, v166, v245
	v_add_f32_e32 v180, v167, v180
	v_add_f32_e32 v169, 1.0, v169
	v_mul_f32_e32 v197, v246, v197
	v_rcp_f32_e32 v169, v169
	v_mul_f32_e32 v180, v180, v197
	v_mul_f32_e32 v197, v100, v165
	v_mul_f32_e32 v165, v84, v165
	v_fmac_f32_e32 v165, v164, v238
	v_fmac_f32_e32 v197, v164, v239
	v_fmac_f32_e32 v165, v172, v166
	v_fmac_f32_e32 v197, v166, v240
	v_add_f32_e32 v164, v167, v165
	v_mul_f32_e32 v165, v168, v169
	v_add_f32_e32 v197, v167, v197
	v_mul_f32_e32 v171, v164, v165
	v_cndmask_b32_e64 v164, v235, v230, s[44:45]
	v_mul_f32_e32 v167, v103, v161
	v_fmac_f32_e32 v167, v164, v160
	v_fmac_f32_e32 v167, v158, v233
	v_add_f32_e32 v164, v159, v167
	v_mul_f32_e32 v167, 0xbfb8aa3b, v164
	v_exp_f32_e32 v167, v167
	v_cndmask_b32_e64 v165, v234, v231, s[44:45]
	v_mul_f32_e32 v166, v123, v155
	v_fmac_f32_e32 v166, v165, v154
	v_fmac_f32_e32 v166, v156, v232
	v_add_f32_e32 v165, v157, v166
	v_add_f32_e32 v166, 1.0, v167
	v_mul_f32_e32 v167, v87, v161
	v_fmac_f32_e32 v167, v160, v228
	v_fmac_f32_e32 v167, v158, v229
	v_add_f32_e32 v167, v159, v167
	v_rcp_f32_e32 v166, v166
	v_mul_f32_e32 v168, 0xbfb8aa3b, v167
	v_exp_f32_e32 v168, v168
	v_cndmask_b32_e64 v163, v237, v163, s[42:43]
	v_mul_f32_e32 v164, v164, v166
	v_mul_f32_e32 v172, v165, v164
	v_add_f32_e32 v165, 1.0, v168
	v_rcp_f32_e32 v165, v165
	v_mul_f32_e32 v164, v115, v155
	v_fmac_f32_e32 v164, v154, v226
	v_fmac_f32_e32 v164, v156, v227
	v_add_f32_e32 v164, v157, v164
	v_mul_f32_e32 v165, v167, v165
	v_mul_f32_e32 v173, v164, v165
	v_mul_f32_e32 v165, v75, v161
	v_mul_f32_e32 v161, v67, v161
	v_fmac_f32_e32 v161, v160, v223
	v_fmac_f32_e32 v165, v160, v224
	v_fmac_f32_e32 v161, v163, v158
	v_fmac_f32_e32 v165, v158, v225
	v_add_f32_e32 v158, v159, v161
	v_add_f32_e32 v165, v159, v165
	v_mul_f32_e32 v159, 0xbfb8aa3b, v158
	v_exp_f32_e32 v159, v159
	v_mul_f32_e32 v164, v99, v155
	v_mul_f32_e32 v155, v83, v155
	v_cndmask_b32_e64 v162, v236, v162, s[42:43]
	v_add_f32_e32 v159, 1.0, v159
	v_rcp_f32_e32 v159, v159
	v_fmac_f32_e32 v155, v154, v220
	v_fmac_f32_e32 v164, v154, v221
	v_fmac_f32_e32 v155, v162, v156
	v_fmac_f32_e32 v164, v156, v222
	v_add_f32_e32 v154, v157, v155
	v_mul_f32_e32 v155, v158, v159
	v_add_f32_e32 v164, v157, v164
	v_mul_f32_e32 v220, v154, v155
	v_cndmask_b32_e64 v154, v215, v210, s[44:45]
	v_mul_f32_e32 v157, v102, v151
	v_fmac_f32_e32 v157, v154, v150
	v_fmac_f32_e32 v157, v148, v213
	v_add_f32_e32 v154, v149, v157
	v_mul_f32_e32 v157, 0xbfb8aa3b, v154
	v_exp_f32_e32 v157, v157
	v_cndmask_b32_e64 v155, v214, v211, s[44:45]
	v_mul_f32_e32 v156, v122, v131
	v_fmac_f32_e32 v156, v155, v130
	v_fmac_f32_e32 v156, v132, v212
	v_add_f32_e32 v155, v133, v156
	v_add_f32_e32 v156, 1.0, v157
	v_mul_f32_e32 v157, v86, v151
	v_fmac_f32_e32 v157, v150, v208
	v_fmac_f32_e32 v157, v148, v209
	v_add_f32_e32 v157, v149, v157
	v_rcp_f32_e32 v156, v156
	v_mul_f32_e32 v158, 0xbfb8aa3b, v157
	v_exp_f32_e32 v158, v158
	v_cndmask_b32_e64 v153, v219, v153, s[42:43]
	v_mul_f32_e32 v154, v154, v156
	v_mul_f32_e32 v208, v155, v154
	v_add_f32_e32 v155, 1.0, v158
	v_rcp_f32_e32 v155, v155
	v_mul_f32_e32 v154, v114, v131
	v_fmac_f32_e32 v154, v130, v206
	v_fmac_f32_e32 v154, v132, v207
	v_add_f32_e32 v154, v133, v154
	v_mul_f32_e32 v155, v157, v155
	v_mul_f32_e32 v206, v154, v155
	v_mul_f32_e32 v155, v74, v151
	v_mul_f32_e32 v151, v66, v151
	v_fmac_f32_e32 v155, v150, v204
	v_fmac_f32_e32 v151, v150, v203
	v_fmac_f32_e32 v155, v148, v205
	v_fmac_f32_e32 v151, v153, v148
	v_mul_f32_e32 v243, 0xbfb8aa3b, v242
	v_add_f32_e32 v155, v149, v155
	v_add_f32_e32 v148, v149, v151
	v_exp_f32_e32 v243, v243
	v_mul_f32_e32 v166, 0xbfb8aa3b, v165
	v_mul_f32_e32 v156, 0xbfb8aa3b, v155
	v_mul_f32_e32 v149, 0xbfb8aa3b, v148
	v_exp_f32_e32 v166, v166
	v_exp_f32_e32 v156, v156
	v_exp_f32_e32 v149, v149
	v_add_f32_e32 v239, 1.0, v243
	v_rcp_f32_e32 v239, v239
	v_add_f32_e32 v166, 1.0, v166
	v_add_f32_e32 v156, 1.0, v156
	v_add_f32_e32 v149, 1.0, v149
	v_rcp_f32_e32 v166, v166
	v_rcp_f32_e32 v156, v156
	v_rcp_f32_e32 v149, v149
	v_mul_f32_e32 v154, v98, v131
	v_mul_f32_e32 v131, v82, v131
	v_cndmask_b32_e64 v152, v218, v152, s[42:43]
	v_fmac_f32_e32 v131, v130, v0
	v_mul_f32_e32 v170, v242, v239
	v_fmac_f32_e32 v131, v152, v132
	v_mul_f32_e32 v170, v197, v170
	v_mul_f32_e32 v160, v165, v166
	v_fmac_f32_e32 v154, v130, v201
	v_mul_f32_e32 v150, v155, v156
	v_add_f32_e32 v0, v133, v131
	v_mul_f32_e32 v130, v148, v149
	ds_read2_b32 v[156:157], v189 offset0:7 offset1:135
	v_add_u32_e32 v197, 28, v189
	v_mul_f32_e32 v221, v164, v160
	v_fmac_f32_e32 v154, v132, v202
	v_mul_f32_e32 v202, v0, v130
	ds_read2_b32 v[130:131], v191 offset0:7 offset1:135
	ds_read2st64_b32 v[158:159], v197 offset0:4 offset1:6
	ds_read2st64_b32 v[160:161], v197 offset0:8 offset1:10
	ds_read2st64_b32 v[162:163], v197 offset0:12 offset1:14
	v_mov_b32_dpp v164, v125 row_ror:1 row_mask:0xf bank_mask:0xf
	v_mov_b32_dpp v165, v105 row_ror:1 row_mask:0xf bank_mask:0xf
	v_mov_b32_e32 v168, v125
	s_waitcnt lgkmcnt(0)
;     DI void operator()(const f32x4 (&acc)[2][2][4][2], const Unit& u, int wr, int wc, int fr, int fq, LAS unsigned char* lds) const {
;     ...
;                         for (int m = 0; m < 4; ++m) {
;                             const float ca = acc[ai][0][m][n][e], cg2 = acc[ai][1][m][n][e];
;                             const float oa_p = (fr == 15) ? acc[ai][0][m == 0 ? 0 : m - 1][n][e] : ca, og_p = (fr == 15) ? acc[ai][1][m == 0 ? 0 : m - 1][n][e] : cg2;
;                             const float oa_n = (fr == 0) ? acc[ai][0][m == 3 ? 3 : m + 1][n][e] : ca, og_n = (fr == 0) ? acc[ai][1][m == 3 ? 3 : m + 1][n][e] : cg2;
;                             ap[m] = __int_as_float(__builtin_amdgcn_mov_dpp(__float_as_int(oa_p), 0x121, 0xF, 0xF, false));
;                             gp[m] = __int_as_float(__builtin_amdgcn_mov_dpp(__float_as_int(og_p), 0x121, 0xF, 0xF, false));
;                             an[m] = __int_as_float(__builtin_amdgcn_mov_dpp(__float_as_int(oa_n), 0x12F, 0xF, 0xF, false));
;                             gn[m] = __int_as_float(__builtin_amdgcn_mov_dpp(__float_as_int(og_n), 0x12F, 0xF, 0xF, false));
;                         }
;                         ap[0] = (fr == 0) ? xpa : ap[0]; gp[0] = (fr == 0) ? xpg : gp[0];
;                         an[3] = (fr == 15) ? xna : an[3]; gn[3] = (fr == 15) ? xng : gn[3];
;                         const float w0a = cwp[0], w1a = cwp[128], w2a = cwp[256], bba = cwp[384];
;                         const float w0g = cwp[512], w1g = cwp[640], w2g = cwp[768], bbg = cwp[896];
; #pragma unroll
;                         for (int m = 0; m < 4; ++m) {
;                             const float av = w0a * ap[m] + w1a * acc[ai][0][m][n][e] + w2a * an[m] + bba;
;                             const float gv = w0g * gp[m] + w1g * acc[ai][1][m][n][e] + w2g * gn[m] + bbg;
;                             o[m][e] = av * siluf_(gv);
;                         }
;                         __builtin_amdgcn_sched_barrier(0);
;                     }
; #pragma unroll
;                     for (int m = 0; m < 4; ++m) {
;                         u32x2 ov; ov[0] = pk_bf16(o[m][0], o[m][1]); ov[1] = pk_bf16(o[m][2], o[m][3]);
;                         *(u32x2*)(ACTb + (unsigned)((wr * 64 + fr + ai * HALF + m * 16) * DFF + cl + 4 * n)) = ov;
;                     }
	v_mov_b32_e32 v167, v160
	v_mov_b32_e32 v169, v105
	v_mov_b32_e32 v160, v157
	v_add_f32_e32 v154, v133, v154
	v_cndmask_b32_e64 v0, v125, v117, s[44:45]
	v_cndmask_b32_e64 v133, v105, v89, s[44:45]
	v_cndmask_b32_e64 v165, v165, v216, s[44:45]
	v_cndmask_b32_e64 v164, v164, v217, s[44:45]
	v_mov_b32_e32 v166, v156
	v_pk_mul_f32 v[156:157], v[168:169], v[160:161]
	v_mov_b32_dpp v132, v0 row_ror:15 row_mask:0xf bank_mask:0xf
	v_mov_b32_dpp v133, v133 row_ror:15 row_mask:0xf bank_mask:0xf
	v_pk_fma_f32 v[156:157], v[164:165], v[166:167], v[156:157]
	v_mov_b32_e32 v164, v158
	v_mov_b32_e32 v165, v162
	v_pk_fma_f32 v[132:133], v[164:165], v[132:133], v[156:157]
	v_mov_b32_e32 v162, v159
	v_pk_add_f32 v[132:133], v[162:163], v[132:133]
	v_cndmask_b32_e64 v0, v117, v125, s[42:43]
	v_mul_f32_e32 v156, 0xbfb8aa3b, v133
	v_exp_f32_e32 v158, v156
	v_cndmask_b32_e64 v149, v89, v105, s[42:43]
	v_mov_b32_e32 v159, v89
	v_mul_f32_e32 v201, v154, v150
	v_add_f32_e32 v158, 1.0, v158
	v_rcp_f32_e32 v168, v158
	v_mov_b32_e32 v158, v117
	v_cndmask_b32_e64 v150, v117, v101, s[44:45]
	v_cndmask_b32_e64 v151, v89, v77, s[44:45]
	v_mov_b32_dpp v148, v0 row_ror:1 row_mask:0xf bank_mask:0xf
	v_mov_b32_dpp v149, v149 row_ror:1 row_mask:0xf bank_mask:0xf
	v_pk_mul_f32 v[158:159], v[158:159], v[160:161]
	v_mov_b32_dpp v150, v150 row_ror:15 row_mask:0xf bank_mask:0xf
	v_mov_b32_dpp v151, v151 row_ror:15 row_mask:0xf bank_mask:0xf
	v_pk_fma_f32 v[148:149], v[166:167], v[148:149], v[158:159]
	v_mul_f32_e32 v133, v133, v168
	v_pk_fma_f32 v[148:149], v[164:165], v[150:151], v[148:149]
	v_mul_f32_e32 v158, v132, v133
	v_pk_add_f32 v[148:149], v[162:163], v[148:149]
	v_cndmask_b32_e64 v0, v101, v117, s[42:43]
	v_mul_f32_e32 v150, 0xbfb8aa3b, v149
	v_exp_f32_e32 v150, v150
	v_cndmask_b32_e64 v153, v77, v89, s[42:43]
	v_mov_b32_e32 v133, v77
	v_cndmask_b32_e64 v154, v101, v85, s[44:45]
	v_add_f32_e32 v132, 1.0, v150
	v_rcp_f32_e32 v159, v132
	v_mov_b32_e32 v132, v101
	v_cndmask_b32_e64 v155, v77, v69, s[44:45]
	v_mov_b32_dpp v152, v0 row_ror:1 row_mask:0xf bank_mask:0xf
	v_mov_b32_dpp v153, v153 row_ror:1 row_mask:0xf bank_mask:0xf
	v_pk_mul_f32 v[132:133], v[132:133], v[160:161]
	v_mov_b32_dpp v154, v154 row_ror:15 row_mask:0xf bank_mask:0xf
	v_mov_b32_dpp v155, v155 row_ror:15 row_mask:0xf bank_mask:0xf
	v_pk_fma_f32 v[132:133], v[166:167], v[152:153], v[132:133]
	v_mov_b32_dpp v151, v69 row_ror:15 row_mask:0xf bank_mask:0xf
	v_pk_fma_f32 v[132:133], v[164:165], v[154:155], v[132:133]
	v_cndmask_b32_e64 v0, v85, v101, s[42:43]
	v_pk_add_f32 v[132:133], v[162:163], v[132:133]
	v_cndmask_b32_e64 v191, v69, v77, s[42:43]
	v_mul_f32_e32 v150, 0xbfb8aa3b, v133
	v_exp_f32_e32 v152, v150
	v_cndmask_b32_e64 v131, v151, v131, s[42:43]
	v_mov_b32_e32 v150, v85
	v_mov_b32_e32 v151, v69
	v_mov_b32_dpp v156, v0 row_ror:1 row_mask:0xf bank_mask:0xf
	v_mov_b32_dpp v157, v191 row_ror:1 row_mask:0xf bank_mask:0xf
	v_mov_b32_dpp v0, v85 row_ror:15 row_mask:0xf bank_mask:0xf
	v_pk_mul_f32 v[150:151], v[150:151], v[160:161]
	v_cndmask_b32_e64 v130, v0, v130, s[42:43]
	v_pk_fma_f32 v[150:151], v[166:167], v[156:157], v[150:151]
	v_mul_f32_e32 v149, v149, v159
	v_pk_fma_f32 v[130:131], v[130:131], v[164:165], v[150:151]
	v_add_f32_e32 v150, 1.0, v152
	v_pk_add_f32 v[130:131], v[162:163], v[130:131]
	v_rcp_f32_e32 v150, v150
	v_mul_f32_e32 v0, 0xbfb8aa3b, v131
	v_exp_f32_e32 v0, v0
	v_mul_f32_e32 v148, v148, v149
	v_mul_f32_e32 v133, v133, v150
	v_mul_f32_e32 v149, v132, v133
	v_add_f32_e32 v0, 1.0, v0
	v_rcp_f32_e32 v0, v0
	s_nop 0
	v_mul_f32_e32 v0, v131, v0
	v_mul_f32_e32 v150, v130, v0
	v_or_b32_e32 v191, 4, v146
	v_add_u32_e32 v0, v191, v190
	v_lshl_add_u64 v[132:133], v[0:1], 1, s[50:51]
	v_add_u32_e32 v0, v191, v198
	v_cvt_pk_bf16_f32 v130, v208, v172
	v_cvt_pk_bf16_f32 v131, v179, v158
	global_store_dwordx2 v[132:133], v[130:131], off
	v_lshl_add_u64 v[132:133], v[0:1], 1, s[50:51]
	v_add_u32_e32 v0, v191, v199
	v_cvt_pk_bf16_f32 v130, v206, v173
	v_cvt_pk_bf16_f32 v131, v180, v148
	global_store_dwordx2 v[132:133], v[130:131], off
	v_lshl_add_u64 v[132:133], v[0:1], 1, s[50:51]
	v_add_u32_e32 v0, v191, v200
	v_cvt_pk_bf16_f32 v130, v201, v221
	v_cvt_pk_bf16_f32 v131, v170, v149
	global_store_dwordx2 v[132:133], v[130:131], off
	v_lshl_add_u64 v[132:133], v[0:1], 1, s[50:51]
	v_cvt_pk_bf16_f32 v130, v202, v220
	v_cvt_pk_bf16_f32 v131, v171, v150
	global_store_dwordx2 v[132:133], v[130:131], off
	s_and_b64 s[46:47], s[54:55], exec
	s_movk_i32 s21, 0x1400
	s_cselect_b32 s21, 0xc00, s21
	v_add_u32_e32 v199, s21, v174
	ds_read2st64_b32 v[152:153], v199 offset1:2
	v_cndmask_b32_e64 v0, 0, 1, s[52:53]
	v_lshl_add_u32 v198, s20, 2, v174
	v_mov_b32_e32 v208, 0
	v_cmp_ne_u32_e64 s[46:47], 1, v0
	s_andn2_b64 vcc, exec, s[52:53]
	v_mov_b32_e32 v211, 0
	s_cbranch_vccnz .LBB0_297
	ds_read_b32 v211, v198

;     DI void operator()(const f32x4 (&acc)[2][2][4][2], const Unit& u, int wr, int wc, int fr, int fq, LAS unsigned char* lds) const {
;     ...
;                 for (int n = 0; n < 2; ++n) {
;                     float o[4][4];
; #pragma unroll
;                     for (int e = 0; e < 4; ++e) {
;                         const LAS float* cwp = CWL + cl + 4 * n + e;
;                         const float xpa = hasp ? xp[4 * n + e] : 0.f, xpg = hasp ? xp[128 + 4 * n + e] : 0.f;
;                         const float xna = hasn ? xn[4 * n + e] : 0.f, xng = hasn ? xn[128 + 4 * n + e] : 0.f;
;                         float ap[4], gp[4], an[4], gn[4];
; #pragma unroll
;                         for (int m = 0; m < 4; ++m) {
;                             const float ca = acc[ai][0][m][n][e], cg2 = acc[ai][1][m][n][e];
;                             const float oa_p = (fr == 15) ? acc[ai][0][m == 0 ? 0 : m - 1][n][e] : ca, og_p = (fr == 15) ? acc[ai][1][m == 0 ? 0 : m - 1][n][e] : cg2;
;                             const float oa_n = (fr == 0) ? acc[ai][0][m == 3 ? 3 : m + 1][n][e] : ca, og_n = (fr == 0) ? acc[ai][1][m == 3 ? 3 : m + 1][n][e] : cg2;
;                             ap[m] = __int_as_float(__builtin_amdgcn_mov_dpp(__float_as_int(oa_p), 0x121, 0xF, 0xF, false));
;                             gp[m] = __int_as_float(__builtin_amdgcn_mov_dpp(__float_as_int(og_p), 0x121, 0xF, 0xF, false));
;                             an[m] = __int_as_float(__builtin_amdgcn_mov_dpp(__float_as_int(oa_n), 0x12F, 0xF, 0xF, false));
;                             gn[m] = __int_as_float(__builtin_amdgcn_mov_dpp(__float_as_int(og_n), 0x12F, 0xF, 0xF, false));
;                         }
;                         ap[0] = (fr == 0) ? xpa : ap[0]; gp[0] = (fr == 0) ? xpg : gp[0];
;                         an[3] = (fr == 15) ? xna : an[3]; gn[3] = (fr == 15) ? xng : gn[3];
;                         const float w0a = cwp[0], w1a = cwp[128], w2a = cwp[256], bba = cwp[384];
;                         const float w0g = cwp[512], w1g = cwp[640], w2g = cwp[768], bbg = cwp[896];
; #pragma unroll
;                         for (int m = 0; m < 4; ++m) {
;                             const float av = w0a * ap[m] + w1a * acc[ai][0][m][n][e] + w2a * an[m] + bba;
;                             const float gv = w0g * gp[m] + w1g * acc[ai][1][m][n][e] + w2g * gn[m] + bbg;
.LBB0_311:
	s_waitcnt lgkmcnt(0)
	v_cndmask_b32_e64 v175, v251, v175, s[44:45]
	v_cndmask_b32_e64 v179, v179, v247, s[42:43]
	v_mul_f32_e32 v247, v44, v173
	v_fmac_f32_e32 v247, v175, v172
	v_fmac_f32_e32 v247, v170, v249
	v_add_f32_e32 v175, v171, v247
	v_mul_f32_e32 v247, 0xbfb8aa3b, v175
	v_exp_f32_e32 v247, v247
	v_cndmask_b32_e64 v174, v250, v174, s[44:45]
	v_cndmask_b32_e64 v180, v180, v246, s[42:43]
	v_mul_f32_e32 v246, v64, v169
	v_fmac_f32_e32 v246, v174, v168
	v_fmac_f32_e32 v246, v166, v248
	v_add_f32_e32 v174, v167, v246
	v_add_f32_e32 v246, 1.0, v247
	v_rcp_f32_e32 v246, v246
	v_mul_f32_e32 v247, v28, v173
	v_fmac_f32_e32 v247, v172, v244
	v_fmac_f32_e32 v247, v170, v245
	v_mul_f32_e32 v175, v175, v246
	v_mul_f32_e32 v174, v174, v175
	v_mul_f32_e32 v175, v56, v169
	v_add_f32_e32 v244, v171, v247
	v_fmac_f32_e32 v175, v168, v242
	v_mul_f32_e32 v245, 0xbfb8aa3b, v244
	v_fmac_f32_e32 v175, v166, v243
	v_mul_f32_e32 v243, v16, v173
	v_mul_f32_e32 v173, v8, v173
	v_exp_f32_e32 v245, v245
	v_fmac_f32_e32 v173, v172, v238
	v_fmac_f32_e32 v243, v172, v240
	v_fmac_f32_e32 v173, v180, v170
	v_fmac_f32_e32 v243, v170, v241
	v_add_f32_e32 v170, v171, v173
	v_add_f32_e32 v240, v171, v243
	v_mul_f32_e32 v171, 0xbfb8aa3b, v170
	v_add_f32_e32 v245, 1.0, v245
	v_exp_f32_e32 v171, v171
	v_rcp_f32_e32 v245, v245
	v_add_f32_e32 v175, v167, v175
	v_cndmask_b32_e64 v165, v233, v165, s[44:45]
	v_add_f32_e32 v171, 1.0, v171
	v_mul_f32_e32 v242, v244, v245
	v_rcp_f32_e32 v171, v171
	v_mul_f32_e32 v175, v175, v242
	v_mul_f32_e32 v242, v48, v169
	v_mul_f32_e32 v169, v32, v169
	v_fmac_f32_e32 v242, v168, v237
	v_fmac_f32_e32 v169, v168, v236
	v_fmac_f32_e32 v242, v166, v239
	v_fmac_f32_e32 v169, v179, v166
	v_add_f32_e32 v237, v167, v242
	v_add_f32_e32 v166, v167, v169
	v_mul_f32_e32 v167, v170, v171
	v_mul_f32_e32 v170, v43, v163
	v_fmac_f32_e32 v170, v165, v162
	v_fmac_f32_e32 v170, v160, v231
	v_add_f32_e32 v165, v161, v170
	v_mul_f32_e32 v170, 0xbfb8aa3b, v165
	v_exp_f32_e32 v170, v170
	v_cndmask_b32_e64 v164, v232, v164, s[44:45]
	v_mul_f32_e32 v169, v63, v159
	v_fmac_f32_e32 v169, v164, v158
	v_fmac_f32_e32 v169, v156, v230
	v_add_f32_e32 v164, v157, v169
	v_add_f32_e32 v169, 1.0, v170
	v_mul_f32_e32 v170, v27, v163
	v_fmac_f32_e32 v170, v162, v226
	v_fmac_f32_e32 v170, v160, v227
	v_add_f32_e32 v170, v161, v170
	v_rcp_f32_e32 v169, v169
	v_mul_f32_e32 v171, 0xbfb8aa3b, v170
	v_exp_f32_e32 v171, v171
	v_mul_f32_e32 v168, v166, v167
	v_mul_f32_e32 v165, v165, v169
	v_mul_f32_e32 v169, v164, v165
	v_add_f32_e32 v165, 1.0, v171
	v_rcp_f32_e32 v165, v165
	v_mul_f32_e32 v164, v55, v159
	v_fmac_f32_e32 v164, v158, v224
	v_fmac_f32_e32 v164, v156, v225
	v_add_f32_e32 v164, v157, v164
	v_mul_f32_e32 v165, v170, v165
	v_mul_f32_e32 v170, v164, v165
	v_mul_f32_e32 v164, v47, v159
	v_mul_f32_e32 v159, v31, v159
	v_cndmask_b32_e64 v166, v234, v229, s[42:43]
	v_fmac_f32_e32 v159, v158, v218
	v_mul_f32_e32 v165, v15, v163
	v_fmac_f32_e32 v164, v158, v219
	v_mul_f32_e32 v163, v7, v163
	v_fmac_f32_e32 v159, v166, v156
	v_cndmask_b32_e64 v167, v235, v228, s[42:43]
	v_fmac_f32_e32 v164, v156, v221
	v_fmac_f32_e32 v163, v162, v220
	v_add_f32_e32 v156, v157, v159
	v_cndmask_b32_e64 v153, v215, v153, s[44:45]
	v_mul_f32_e32 v159, v42, v151
	v_fmac_f32_e32 v165, v162, v222
	v_fmac_f32_e32 v163, v167, v160
	v_fmac_f32_e32 v159, v153, v150
	v_fmac_f32_e32 v165, v160, v223
	v_add_f32_e32 v160, v161, v163
	v_fmac_f32_e32 v159, v148, v213
	v_add_f32_e32 v165, v161, v165
	v_mul_f32_e32 v161, 0xbfb8aa3b, v160
	v_add_f32_e32 v153, v149, v159
	v_exp_f32_e32 v161, v161
	v_mul_f32_e32 v159, 0xbfb8aa3b, v153
	v_exp_f32_e32 v159, v159
	v_cndmask_b32_e64 v152, v214, v152, s[44:45]
	v_mul_f32_e32 v158, v62, v133
	v_fmac_f32_e32 v158, v152, v132
	v_add_f32_e32 v161, 1.0, v161
	v_fmac_f32_e32 v158, v130, v212
	v_rcp_f32_e32 v161, v161
	v_add_f32_e32 v152, v131, v158
	v_add_f32_e32 v158, 1.0, v159
	v_mul_f32_e32 v159, v26, v151
	v_fmac_f32_e32 v159, v150, v209
	v_fmac_f32_e32 v159, v148, v210
	v_add_f32_e32 v159, v149, v159
	v_add_f32_e32 v164, v157, v164
	v_mul_f32_e32 v157, v160, v161
	v_rcp_f32_e32 v158, v158
	v_mul_f32_e32 v160, 0xbfb8aa3b, v159
	v_exp_f32_e32 v160, v160
	v_mul_f32_e32 v171, 0xbfb8aa3b, v165
	v_mul_f32_e32 v153, v153, v158
	v_mul_f32_e32 v179, v152, v153
	v_add_f32_e32 v153, 1.0, v160
	v_rcp_f32_e32 v153, v153
	v_mul_f32_e32 v152, v54, v133
	v_fmac_f32_e32 v152, v132, v206
	v_fmac_f32_e32 v152, v130, v207
	v_add_f32_e32 v152, v131, v152
	v_mul_f32_e32 v153, v159, v153
	v_mul_f32_e32 v180, v152, v153
	v_mul_f32_e32 v153, v14, v151
	v_fmac_f32_e32 v153, v150, v204
	v_fmac_f32_e32 v153, v148, v205
	v_add_f32_e32 v153, v149, v153
	v_exp_f32_e32 v171, v171
	v_mul_f32_e32 v158, 0xbfb8aa3b, v153
	v_mul_f32_e32 v151, v6, v151
	v_mul_f32_e32 v173, v156, v157
	v_cndmask_b32_e64 v157, v217, v208, s[42:43]
	v_exp_f32_e32 v158, v158
	v_fmac_f32_e32 v151, v150, v202
	v_fmac_f32_e32 v151, v157, v148
	v_add_f32_e32 v148, v149, v151
	v_add_f32_e32 v171, 1.0, v171
	v_mul_f32_e32 v149, 0xbfb8aa3b, v148
	v_rcp_f32_e32 v171, v171
	v_add_f32_e32 v158, 1.0, v158
	v_exp_f32_e32 v149, v149
	v_rcp_f32_e32 v158, v158
	v_mul_f32_e32 v152, v46, v133
	v_mul_f32_e32 v133, v30, v133
	v_mul_f32_e32 v162, v165, v171
	v_cndmask_b32_e64 v156, v216, v211, s[42:43]
	v_add_f32_e32 v149, 1.0, v149
	v_fmac_f32_e32 v133, v132, v0
	v_mul_f32_e32 v171, v164, v162
	v_mul_f32_e32 v150, v153, v158
	v_rcp_f32_e32 v149, v149
	v_fmac_f32_e32 v133, v156, v130
	ds_read2_b32 v[156:157], v189 offset0:3 offset1:131
	ds_read2st64_b32 v[158:159], v193 offset0:4 offset1:6
	ds_read2st64_b32 v[160:161], v193 offset0:8 offset1:10
	ds_read2st64_b32 v[162:163], v193 offset0:12 offset1:14
	v_fmac_f32_e32 v152, v132, v201
	v_mov_b32_dpp v165, v45 row_ror:1 row_mask:0xf bank_mask:0xf
	v_fmac_f32_e32 v152, v130, v203
	v_add_f32_e32 v0, v131, v133
	v_mul_f32_e32 v130, v148, v149
	v_mov_b32_dpp v164, v65 row_ror:1 row_mask:0xf bank_mask:0xf
	v_cndmask_b32_e64 v155, v165, v155, s[44:45]
	s_waitcnt lgkmcnt(0)
;     DI void operator()(const f32x4 (&acc)[2][2][4][2], const Unit& u, int wr, int wc, int fr, int fq, LAS unsigned char* lds) const {
;     ...
;                         for (int m = 0; m < 4; ++m) {
;                             const float ca = acc[ai][0][m][n][e], cg2 = acc[ai][1][m][n][e];
;                             const float oa_p = (fr == 15) ? acc[ai][0][m == 0 ? 0 : m - 1][n][e] : ca, og_p = (fr == 15) ? acc[ai][1][m == 0 ? 0 : m - 1][n][e] : cg2;
;                             const float oa_n = (fr == 0) ? acc[ai][0][m == 3 ? 3 : m + 1][n][e] : ca, og_n = (fr == 0) ? acc[ai][1][m == 3 ? 3 : m + 1][n][e] : cg2;
;                             ap[m] = __int_as_float(__builtin_amdgcn_mov_dpp(__float_as_int(oa_p), 0x121, 0xF, 0xF, false));
;                             gp[m] = __int_as_float(__builtin_amdgcn_mov_dpp(__float_as_int(og_p), 0x121, 0xF, 0xF, false));
;                             an[m] = __int_as_float(__builtin_amdgcn_mov_dpp(__float_as_int(oa_n), 0x12F, 0xF, 0xF, false));
;                             gn[m] = __int_as_float(__builtin_amdgcn_mov_dpp(__float_as_int(og_n), 0x12F, 0xF, 0xF, false));
;                         }
;                         ap[0] = (fr == 0) ? xpa : ap[0]; gp[0] = (fr == 0) ? xpg : gp[0];
;                         an[3] = (fr == 15) ? xna : an[3]; gn[3] = (fr == 15) ? xng : gn[3];
;                         const float w0a = cwp[0], w1a = cwp[128], w2a = cwp[256], bba = cwp[384];
;                         const float w0g = cwp[512], w1g = cwp[640], w2g = cwp[768], bbg = cwp[896];
; #pragma unroll
;                         for (int m = 0; m < 4; ++m) {
;                             const float av = w0a * ap[m] + w1a * acc[ai][0][m][n][e] + w2a * an[m] + bba;
;                             const float gv = w0g * gp[m] + w1g * acc[ai][1][m][n][e] + w2g * gn[m] + bbg;
;                             o[m][e] = av * siluf_(gv);
;                         }
;                         __builtin_amdgcn_sched_barrier(0);
;                     }
; #pragma unroll
;                     for (int m = 0; m < 4; ++m) {
;                         u32x2 ov; ov[0] = pk_bf16(o[m][0], o[m][1]); ov[1] = pk_bf16(o[m][2], o[m][3]);
;                         *(u32x2*)(ACTb + (unsigned)((wr * 64 + fr + ai * HALF + m * 16) * DFF + cl + 4 * n)) = ov;
;                     }
	v_mov_b32_e32 v165, v160
	v_mov_b32_e32 v166, v65
	v_mov_b32_e32 v167, v45
	v_mov_b32_e32 v160, v157
	v_add_f32_e32 v152, v131, v152
	v_mul_f32_e32 v202, v0, v130
	v_cndmask_b32_e64 v0, v65, v57, s[44:45]
	v_cndmask_b32_e64 v131, v45, v29, s[44:45]
	v_cndmask_b32_e64 v154, v164, v154, s[44:45]
	v_mov_b32_e32 v164, v156
	v_pk_mul_f32 v[156:157], v[166:167], v[160:161]
	v_mov_b32_dpp v130, v0 row_ror:15 row_mask:0xf bank_mask:0xf
	v_mov_b32_dpp v131, v131 row_ror:15 row_mask:0xf bank_mask:0xf
	v_pk_fma_f32 v[154:155], v[154:155], v[164:165], v[156:157]
	v_mov_b32_e32 v156, v158
	v_mov_b32_e32 v157, v162
	v_pk_fma_f32 v[130:131], v[156:157], v[130:131], v[154:155]
	v_mov_b32_e32 v162, v159
	v_pk_add_f32 v[130:131], v[162:163], v[130:131]
	v_cndmask_b32_e64 v0, v57, v65, s[42:43]
	v_mul_f32_e32 v154, 0xbfb8aa3b, v131
	v_exp_f32_e32 v158, v154
	v_cndmask_b32_e64 v133, v29, v45, s[42:43]
	v_mov_b32_e32 v159, v29
	v_cndmask_b32_e64 v148, v57, v49, s[44:45]
	v_add_f32_e32 v158, 1.0, v158
	v_rcp_f32_e32 v166, v158
	v_mov_b32_e32 v158, v57
	v_cndmask_b32_e64 v149, v29, v17, s[44:45]
	v_mov_b32_dpp v132, v0 row_ror:1 row_mask:0xf bank_mask:0xf
	v_mov_b32_dpp v133, v133 row_ror:1 row_mask:0xf bank_mask:0xf
	v_pk_mul_f32 v[158:159], v[158:159], v[160:161]
	v_mov_b32_dpp v148, v148 row_ror:15 row_mask:0xf bank_mask:0xf
	v_mov_b32_dpp v149, v149 row_ror:15 row_mask:0xf bank_mask:0xf
	v_pk_fma_f32 v[132:133], v[164:165], v[132:133], v[158:159]
	v_mul_f32_e32 v131, v131, v166
	v_pk_fma_f32 v[132:133], v[156:157], v[148:149], v[132:133]
	v_mul_f32_e32 v158, v130, v131
	v_pk_add_f32 v[132:133], v[162:163], v[132:133]
	v_cndmask_b32_e64 v0, v49, v57, s[42:43]
	v_mul_f32_e32 v148, 0xbfb8aa3b, v133
	v_exp_f32_e32 v148, v148
	v_cndmask_b32_e64 v151, v17, v29, s[42:43]
	v_mov_b32_e32 v131, v17
	v_mul_f32_e32 v201, v152, v150
	v_add_f32_e32 v130, 1.0, v148
	v_rcp_f32_e32 v159, v130
	v_mov_b32_e32 v130, v49
	v_cndmask_b32_e64 v152, v49, v33, s[44:45]
	v_cndmask_b32_e64 v153, v17, v9, s[44:45]
	v_mov_b32_dpp v150, v0 row_ror:1 row_mask:0xf bank_mask:0xf
	v_mov_b32_dpp v151, v151 row_ror:1 row_mask:0xf bank_mask:0xf
	v_pk_mul_f32 v[130:131], v[130:131], v[160:161]
	v_mov_b32_dpp v152, v152 row_ror:15 row_mask:0xf bank_mask:0xf
	v_mov_b32_dpp v153, v153 row_ror:15 row_mask:0xf bank_mask:0xf
	v_pk_fma_f32 v[130:131], v[164:165], v[150:151], v[130:131]
	v_cndmask_b32_e64 v0, v33, v49, s[42:43]
	v_pk_fma_f32 v[130:131], v[156:157], v[152:153], v[130:131]
	v_cndmask_b32_e64 v203, v9, v17, s[42:43]
	v_pk_add_f32 v[130:131], v[162:163], v[130:131]
	v_mov_b32_e32 v150, v33
	v_mov_b32_e32 v151, v9
	v_mov_b32_dpp v154, v0 row_ror:1 row_mask:0xf bank_mask:0xf
	v_mov_b32_dpp v155, v203 row_ror:1 row_mask:0xf bank_mask:0xf
	v_mov_b32_dpp v0, v33 row_ror:15 row_mask:0xf bank_mask:0xf
	v_mov_b32_dpp v149, v9 row_ror:15 row_mask:0xf bank_mask:0xf
	v_mul_f32_e32 v148, 0xbfb8aa3b, v131
	v_pk_mul_f32 v[150:151], v[150:151], v[160:161]
	v_exp_f32_e32 v152, v148
	v_cndmask_b32_e64 v149, v149, v192, s[42:43]
	v_cndmask_b32_e64 v148, v0, v200, s[42:43]
	v_pk_fma_f32 v[150:151], v[164:165], v[154:155], v[150:151]
	v_mul_f32_e32 v241, 0xbfb8aa3b, v240
	v_pk_fma_f32 v[148:149], v[148:149], v[156:157], v[150:151]
	v_exp_f32_e32 v241, v241
	v_pk_add_f32 v[148:149], v[162:163], v[148:149]
	v_add_f32_e32 v150, 1.0, v152
	v_mul_f32_e32 v0, 0xbfb8aa3b, v149
	v_exp_f32_e32 v0, v0
	v_add_f32_e32 v239, 1.0, v241
	v_rcp_f32_e32 v239, v239
	v_rcp_f32_e32 v150, v150
	v_add_f32_e32 v0, 1.0, v0
	v_rcp_f32_e32 v0, v0
	v_mul_f32_e32 v172, v240, v239
	v_mul_f32_e32 v133, v133, v159
	v_mul_f32_e32 v131, v131, v150
	v_mul_f32_e32 v0, v149, v0
	v_mul_f32_e32 v172, v237, v172
	v_mul_f32_e32 v151, v132, v133
	v_mul_f32_e32 v150, v130, v131
	v_mul_f32_e32 v148, v148, v0
	v_add_u32_e32 v192, 0x58000, v190
	v_add_u32_e32 v0, v192, v146
	v_add_u32_e32 v193, 0x63000, v190
	v_lshl_add_u64 v[132:133], v[0:1], 1, s[50:51]
	v_add_u32_e32 v0, v193, v146
	v_add_u32_e32 v200, 0x6e000, v190
	v_cvt_pk_bf16_f32 v130, v179, v169
	v_cvt_pk_bf16_f32 v131, v174, v158
	global_store_dwordx2 v[132:133], v[130:131], off
	v_lshl_add_u64 v[132:133], v[0:1], 1, s[50:51]
	v_add_u32_e32 v0, v200, v146
	v_add_u32_e32 v190, 0x79000, v190
	v_cvt_pk_bf16_f32 v130, v180, v170
	v_cvt_pk_bf16_f32 v131, v175, v151
	global_store_dwordx2 v[132:133], v[130:131], off
	v_lshl_add_u64 v[132:133], v[0:1], 1, s[50:51]
	v_add_u32_e32 v0, v190, v146
	v_cvt_pk_bf16_f32 v130, v201, v171
	v_cvt_pk_bf16_f32 v131, v172, v150
	global_store_dwordx2 v[132:133], v[130:131], off
	v_lshl_add_u64 v[132:133], v[0:1], 1, s[50:51]
	v_cvt_pk_bf16_f32 v130, v202, v173
	v_cvt_pk_bf16_f32 v131, v168, v148
	global_store_dwordx2 v[132:133], v[130:131], off
	ds_read2_b32 v[152:153], v199 offset0:4 offset1:132
	v_mov_b32_e32 v210, 0
	s_and_b64 vcc, exec, s[46:47]
	v_mov_b32_e32 v211, 0
	s_cbranch_vccnz .LBB0_313
	ds_read_b32 v211, v198 offset:16

;     DI void operator()(const f32x4 (&acc)[2][2][4][2], const Unit& u, int wr, int wc, int fr, int fq, LAS unsigned char* lds) const {
;     ...
;                 for (int n = 0; n < 2; ++n) {
;                     float o[4][4];
; #pragma unroll
;                     for (int e = 0; e < 4; ++e) {
;                         const LAS float* cwp = CWL + cl + 4 * n + e;
;                         const float xpa = hasp ? xp[4 * n + e] : 0.f, xpg = hasp ? xp[128 + 4 * n + e] : 0.f;
;                         const float xna = hasn ? xn[4 * n + e] : 0.f, xng = hasn ? xn[128 + 4 * n + e] : 0.f;
;                         float ap[4], gp[4], an[4], gn[4];
; #pragma unroll
;                         for (int m = 0; m < 4; ++m) {
;                             const float ca = acc[ai][0][m][n][e], cg2 = acc[ai][1][m][n][e];
;                             const float oa_p = (fr == 15) ? acc[ai][0][m == 0 ? 0 : m - 1][n][e] : ca, og_p = (fr == 15) ? acc[ai][1][m == 0 ? 0 : m - 1][n][e] : cg2;
;                             const float oa_n = (fr == 0) ? acc[ai][0][m == 3 ? 3 : m + 1][n][e] : ca, og_n = (fr == 0) ? acc[ai][1][m == 3 ? 3 : m + 1][n][e] : cg2;
;                             ap[m] = __int_as_float(__builtin_amdgcn_mov_dpp(__float_as_int(oa_p), 0x121, 0xF, 0xF, false));
;                             gp[m] = __int_as_float(__builtin_amdgcn_mov_dpp(__float_as_int(og_p), 0x121, 0xF, 0xF, false));
;                             an[m] = __int_as_float(__builtin_amdgcn_mov_dpp(__float_as_int(oa_n), 0x12F, 0xF, 0xF, false));
;                             gn[m] = __int_as_float(__builtin_amdgcn_mov_dpp(__float_as_int(og_n), 0x12F, 0xF, 0xF, false));
;                         }
;                         ap[0] = (fr == 0) ? xpa : ap[0]; gp[0] = (fr == 0) ? xpg : gp[0];
;                         an[3] = (fr == 15) ? xna : an[3]; gn[3] = (fr == 15) ? xng : gn[3];
;                         const float w0a = cwp[0], w1a = cwp[128], w2a = cwp[256], bba = cwp[384];
;                         const float w0g = cwp[512], w1g = cwp[640], w2g = cwp[768], bbg = cwp[896];
; #pragma unroll
;                         for (int m = 0; m < 4; ++m) {
;                             const float av = w0a * ap[m] + w1a * acc[ai][0][m][n][e] + w2a * an[m] + bba;
;                             const float gv = w0g * gp[m] + w1g * acc[ai][1][m][n][e] + w2g * gn[m] + bbg;
.LBB0_327:
	s_waitcnt lgkmcnt(0)
	v_cndmask_b32_e64 v175, v250, v175, s[44:45]
	v_mul_f32_e32 v199, v36, v173
	v_fmac_f32_e32 v199, v175, v172
	v_fmac_f32_e32 v199, v170, v248
	v_add_f32_e32 v175, v171, v199
	v_mul_f32_e32 v199, 0xbfb8aa3b, v175
	v_exp_f32_e32 v199, v199
	v_cndmask_b32_e64 v174, v249, v174, s[44:45]
	v_mul_f32_e32 v198, v60, v169
	v_fmac_f32_e32 v198, v174, v168
	v_fmac_f32_e32 v198, v166, v247
	v_add_f32_e32 v174, v167, v198
	v_add_f32_e32 v198, 1.0, v199
	v_mul_f32_e32 v199, v20, v173
	v_fmac_f32_e32 v199, v172, v243
	v_fmac_f32_e32 v199, v170, v244
	v_add_f32_e32 v199, v171, v199
	v_mul_f32_e32 v243, 0xbfb8aa3b, v199
	v_rcp_f32_e32 v198, v198
	v_exp_f32_e32 v243, v243
	v_cndmask_b32_e64 v180, v180, v245, s[42:43]
	v_cndmask_b32_e64 v179, v179, v246, s[42:43]
	v_mul_f32_e32 v175, v175, v198
	v_add_f32_e32 v198, 1.0, v243
	v_rcp_f32_e32 v198, v198
	v_mul_f32_e32 v174, v174, v175
	v_mul_f32_e32 v175, v52, v169
	v_fmac_f32_e32 v175, v168, v241
	v_mul_f32_e32 v198, v199, v198
	v_mul_f32_e32 v199, v12, v173
	v_mul_f32_e32 v173, v4, v173
	v_fmac_f32_e32 v173, v172, v237
	v_fmac_f32_e32 v199, v172, v239
	v_fmac_f32_e32 v173, v180, v170
	v_fmac_f32_e32 v199, v170, v240
	v_add_f32_e32 v170, v171, v173
	v_add_f32_e32 v199, v171, v199
	v_mul_f32_e32 v171, 0xbfb8aa3b, v170
	v_exp_f32_e32 v171, v171
	v_fmac_f32_e32 v175, v166, v242
	v_add_f32_e32 v175, v167, v175
	v_mul_f32_e32 v175, v175, v198
	v_add_f32_e32 v171, 1.0, v171
	v_rcp_f32_e32 v171, v171
	v_mul_f32_e32 v198, v40, v169
	v_mul_f32_e32 v169, v24, v169
	v_fmac_f32_e32 v198, v168, v236
	v_fmac_f32_e32 v169, v168, v196
	v_fmac_f32_e32 v198, v166, v238
	v_fmac_f32_e32 v169, v179, v166
	v_add_f32_e32 v198, v167, v198
	v_add_f32_e32 v166, v167, v169
	v_mul_f32_e32 v167, v170, v171
	v_cndmask_b32_e64 v165, v233, v165, s[44:45]
	v_mul_f32_e32 v170, v35, v163
	v_fmac_f32_e32 v170, v165, v162
	v_fmac_f32_e32 v170, v160, v231
	v_add_f32_e32 v165, v161, v170
	v_mul_f32_e32 v170, 0xbfb8aa3b, v165
	v_exp_f32_e32 v170, v170
	v_cndmask_b32_e64 v164, v232, v164, s[44:45]
	v_mul_f32_e32 v169, v59, v159
	v_fmac_f32_e32 v169, v164, v158
	v_fmac_f32_e32 v169, v156, v230
	v_add_f32_e32 v164, v157, v169
	v_add_f32_e32 v169, 1.0, v170
	v_mul_f32_e32 v170, v19, v163
	v_fmac_f32_e32 v170, v162, v226
	v_fmac_f32_e32 v170, v160, v227
	v_add_f32_e32 v170, v161, v170
	v_rcp_f32_e32 v169, v169
	v_mul_f32_e32 v171, 0xbfb8aa3b, v170
	v_exp_f32_e32 v171, v171
	v_mul_f32_e32 v168, v166, v167
	v_mul_f32_e32 v165, v165, v169
	v_mul_f32_e32 v169, v164, v165
	v_add_f32_e32 v165, 1.0, v171
	v_rcp_f32_e32 v165, v165
	v_mul_f32_e32 v164, v51, v159
	v_fmac_f32_e32 v164, v158, v224
	v_fmac_f32_e32 v164, v156, v225
	v_add_f32_e32 v164, v157, v164
	v_mul_f32_e32 v165, v170, v165
	v_mul_f32_e32 v170, v164, v165
	v_mul_f32_e32 v164, v39, v159
	v_mul_f32_e32 v159, v23, v159
	v_cndmask_b32_e64 v166, v234, v229, s[42:43]
	v_fmac_f32_e32 v159, v158, v218
	v_mul_f32_e32 v165, v11, v163
	v_fmac_f32_e32 v164, v158, v219
	v_mul_f32_e32 v163, v3, v163
	v_fmac_f32_e32 v159, v166, v156
	v_cndmask_b32_e64 v167, v235, v228, s[42:43]
	v_fmac_f32_e32 v164, v156, v221
	v_fmac_f32_e32 v163, v162, v220
	v_add_f32_e32 v156, v157, v159
	v_cndmask_b32_e64 v153, v215, v153, s[44:45]
	v_mul_f32_e32 v159, v34, v151
	v_fmac_f32_e32 v165, v162, v222
	v_fmac_f32_e32 v163, v167, v160
	v_fmac_f32_e32 v159, v153, v150
	v_fmac_f32_e32 v165, v160, v223
	v_add_f32_e32 v160, v161, v163
	v_fmac_f32_e32 v159, v148, v213
	v_add_f32_e32 v165, v161, v165
	v_mul_f32_e32 v161, 0xbfb8aa3b, v160
	v_add_f32_e32 v153, v149, v159
	v_exp_f32_e32 v161, v161
	v_mul_f32_e32 v159, 0xbfb8aa3b, v153
	v_exp_f32_e32 v159, v159
	v_cndmask_b32_e64 v152, v214, v152, s[44:45]
	v_mul_f32_e32 v158, v58, v133
	v_fmac_f32_e32 v158, v152, v132
	v_add_f32_e32 v161, 1.0, v161
	v_fmac_f32_e32 v158, v130, v212
	v_rcp_f32_e32 v161, v161
	v_add_f32_e32 v152, v131, v158
	v_add_f32_e32 v158, 1.0, v159
	v_mul_f32_e32 v159, v18, v151
	v_fmac_f32_e32 v159, v150, v208
	v_fmac_f32_e32 v159, v148, v209
	v_add_f32_e32 v159, v149, v159
	v_add_f32_e32 v164, v157, v164
	v_mul_f32_e32 v157, v160, v161
	v_rcp_f32_e32 v158, v158
	v_mul_f32_e32 v160, 0xbfb8aa3b, v159
	v_exp_f32_e32 v160, v160
	v_mul_f32_e32 v171, 0xbfb8aa3b, v165
	v_mul_f32_e32 v153, v153, v158
	v_mul_f32_e32 v179, v152, v153
	v_add_f32_e32 v153, 1.0, v160
	v_rcp_f32_e32 v153, v153
	v_mul_f32_e32 v152, v50, v133
	v_fmac_f32_e32 v152, v132, v206
	v_fmac_f32_e32 v152, v130, v207
	v_add_f32_e32 v152, v131, v152
	v_mul_f32_e32 v153, v159, v153
	v_mul_f32_e32 v180, v152, v153
	v_mul_f32_e32 v153, v10, v151
	v_fmac_f32_e32 v153, v150, v204
	v_fmac_f32_e32 v153, v148, v205
	v_add_f32_e32 v153, v149, v153
	v_exp_f32_e32 v171, v171
	v_mul_f32_e32 v158, 0xbfb8aa3b, v153
	v_mul_f32_e32 v151, v2, v151
	v_mul_f32_e32 v173, v156, v157
	v_cndmask_b32_e64 v157, v217, v210, s[42:43]
	v_exp_f32_e32 v158, v158
	v_fmac_f32_e32 v151, v150, v202
	v_fmac_f32_e32 v151, v157, v148
	v_add_f32_e32 v148, v149, v151
	v_mul_f32_e32 v239, 0xbfb8aa3b, v199
	v_add_f32_e32 v171, 1.0, v171
	v_mul_f32_e32 v149, 0xbfb8aa3b, v148
	v_exp_f32_e32 v239, v239
	v_rcp_f32_e32 v171, v171
	v_add_f32_e32 v158, 1.0, v158
	v_exp_f32_e32 v149, v149
	v_rcp_f32_e32 v158, v158
	v_mul_f32_e32 v152, v38, v133
	v_mul_f32_e32 v133, v22, v133
	v_add_f32_e32 v236, 1.0, v239
	v_mul_f32_e32 v162, v165, v171
	v_cndmask_b32_e64 v156, v216, v211, s[42:43]
	v_add_f32_e32 v149, 1.0, v149
	v_fmac_f32_e32 v133, v132, v0
	v_rcp_f32_e32 v236, v236
	v_mul_f32_e32 v171, v164, v162
	v_mul_f32_e32 v150, v153, v158
	v_rcp_f32_e32 v149, v149
	v_fmac_f32_e32 v133, v156, v130
	ds_read2_b32 v[156:157], v189 offset0:7 offset1:135
	ds_read2st64_b32 v[158:159], v197 offset0:4 offset1:6
	ds_read2st64_b32 v[160:161], v197 offset0:8 offset1:10
	ds_read2st64_b32 v[162:163], v197 offset0:12 offset1:14
	v_fmac_f32_e32 v152, v132, v201
	v_mov_b32_dpp v165, v37 row_ror:1 row_mask:0xf bank_mask:0xf
	v_mul_f32_e32 v172, v199, v236
	v_fmac_f32_e32 v152, v130, v203
	v_add_f32_e32 v0, v131, v133
	v_mul_f32_e32 v130, v148, v149
	v_mov_b32_dpp v164, v61 row_ror:1 row_mask:0xf bank_mask:0xf
	v_cndmask_b32_e64 v155, v165, v155, s[44:45]
	s_waitcnt lgkmcnt(0)
;     DI void operator()(const f32x4 (&acc)[2][2][4][2], const Unit& u, int wr, int wc, int fr, int fq, LAS unsigned char* lds) const {
;     ...
;                         for (int m = 0; m < 4; ++m) {
;                             const float ca = acc[ai][0][m][n][e], cg2 = acc[ai][1][m][n][e];
;                             const float oa_p = (fr == 15) ? acc[ai][0][m == 0 ? 0 : m - 1][n][e] : ca, og_p = (fr == 15) ? acc[ai][1][m == 0 ? 0 : m - 1][n][e] : cg2;
;                             const float oa_n = (fr == 0) ? acc[ai][0][m == 3 ? 3 : m + 1][n][e] : ca, og_n = (fr == 0) ? acc[ai][1][m == 3 ? 3 : m + 1][n][e] : cg2;
;                             ap[m] = __int_as_float(__builtin_amdgcn_mov_dpp(__float_as_int(oa_p), 0x121, 0xF, 0xF, false));
;                             gp[m] = __int_as_float(__builtin_amdgcn_mov_dpp(__float_as_int(og_p), 0x121, 0xF, 0xF, false));
;                             an[m] = __int_as_float(__builtin_amdgcn_mov_dpp(__float_as_int(oa_n), 0x12F, 0xF, 0xF, false));
;                             gn[m] = __int_as_float(__builtin_amdgcn_mov_dpp(__float_as_int(og_n), 0x12F, 0xF, 0xF, false));
;                         }
;                         ap[0] = (fr == 0) ? xpa : ap[0]; gp[0] = (fr == 0) ? xpg : gp[0];
;                         an[3] = (fr == 15) ? xna : an[3]; gn[3] = (fr == 15) ? xng : gn[3];
;                         const float w0a = cwp[0], w1a = cwp[128], w2a = cwp[256], bba = cwp[384];
;                         const float w0g = cwp[512], w1g = cwp[640], w2g = cwp[768], bbg = cwp[896];
; #pragma unroll
;                         for (int m = 0; m < 4; ++m) {
;                             const float av = w0a * ap[m] + w1a * acc[ai][0][m][n][e] + w2a * an[m] + bba;
;                             const float gv = w0g * gp[m] + w1g * acc[ai][1][m][n][e] + w2g * gn[m] + bbg;
;                             o[m][e] = av * siluf_(gv);
;                         }
;                         __builtin_amdgcn_sched_barrier(0);
;                     }
; #pragma unroll
;                     for (int m = 0; m < 4; ++m) {
;                         u32x2 ov; ov[0] = pk_bf16(o[m][0], o[m][1]); ov[1] = pk_bf16(o[m][2], o[m][3]);
;                         *(u32x2*)(ACTb + (unsigned)((wr * 64 + fr + ai * HALF + m * 16) * DFF + cl + 4 * n)) = ov;
;                     }
	v_mov_b32_e32 v165, v160
	v_mov_b32_e32 v166, v61
	v_mov_b32_e32 v167, v37
	v_mov_b32_e32 v160, v157
	v_mul_f32_e32 v172, v198, v172
	v_add_f32_e32 v152, v131, v152
	v_mul_f32_e32 v198, v0, v130
	v_cndmask_b32_e64 v0, v61, v53, s[44:45]
	v_cndmask_b32_e64 v131, v37, v21, s[44:45]
	v_cndmask_b32_e64 v154, v164, v154, s[44:45]
	v_mov_b32_e32 v164, v156
	v_pk_mul_f32 v[156:157], v[166:167], v[160:161]
	v_mov_b32_dpp v130, v0 row_ror:15 row_mask:0xf bank_mask:0xf
	v_mov_b32_dpp v131, v131 row_ror:15 row_mask:0xf bank_mask:0xf
	v_pk_fma_f32 v[154:155], v[154:155], v[164:165], v[156:157]
	v_mov_b32_e32 v156, v158
	v_mov_b32_e32 v157, v162
	v_pk_fma_f32 v[130:131], v[156:157], v[130:131], v[154:155]
	v_mov_b32_e32 v162, v159
	v_pk_add_f32 v[130:131], v[162:163], v[130:131]
	v_cndmask_b32_e64 v0, v53, v61, s[42:43]
	v_mul_f32_e32 v154, 0xbfb8aa3b, v131
	v_exp_f32_e32 v158, v154
	v_cndmask_b32_e64 v133, v21, v37, s[42:43]
	v_mov_b32_e32 v159, v21
	v_cndmask_b32_e64 v148, v53, v41, s[44:45]
	v_add_f32_e32 v158, 1.0, v158
	v_rcp_f32_e32 v166, v158
	v_mov_b32_e32 v158, v53
	v_cndmask_b32_e64 v149, v21, v13, s[44:45]
	v_mov_b32_dpp v132, v0 row_ror:1 row_mask:0xf bank_mask:0xf
	v_mov_b32_dpp v133, v133 row_ror:1 row_mask:0xf bank_mask:0xf
	v_pk_mul_f32 v[158:159], v[158:159], v[160:161]
	v_mov_b32_dpp v148, v148 row_ror:15 row_mask:0xf bank_mask:0xf
	v_mov_b32_dpp v149, v149 row_ror:15 row_mask:0xf bank_mask:0xf
	v_pk_fma_f32 v[132:133], v[164:165], v[132:133], v[158:159]
	v_mul_f32_e32 v131, v131, v166
	v_pk_fma_f32 v[132:133], v[156:157], v[148:149], v[132:133]
	v_mul_f32_e32 v158, v130, v131
	v_pk_add_f32 v[132:133], v[162:163], v[132:133]
	v_cndmask_b32_e64 v0, v41, v53, s[42:43]
	v_mul_f32_e32 v148, 0xbfb8aa3b, v133
	v_exp_f32_e32 v148, v148
	v_cndmask_b32_e64 v151, v13, v21, s[42:43]
	v_mov_b32_e32 v131, v13
	v_mul_f32_e32 v196, v152, v150
	v_add_f32_e32 v130, 1.0, v148
	v_rcp_f32_e32 v159, v130
	v_mov_b32_e32 v130, v41
	v_cndmask_b32_e64 v152, v41, v25, s[44:45]
	v_cndmask_b32_e64 v153, v13, v5, s[44:45]
	v_mov_b32_dpp v150, v0 row_ror:1 row_mask:0xf bank_mask:0xf
	v_mov_b32_dpp v151, v151 row_ror:1 row_mask:0xf bank_mask:0xf
	v_pk_mul_f32 v[130:131], v[130:131], v[160:161]
	v_mov_b32_dpp v152, v152 row_ror:15 row_mask:0xf bank_mask:0xf
	v_mov_b32_dpp v153, v153 row_ror:15 row_mask:0xf bank_mask:0xf
	v_pk_fma_f32 v[130:131], v[164:165], v[150:151], v[130:131]
	v_cndmask_b32_e64 v0, v25, v41, s[42:43]
	v_pk_fma_f32 v[130:131], v[156:157], v[152:153], v[130:131]
	v_cndmask_b32_e64 v199, v5, v13, s[42:43]
	v_pk_add_f32 v[130:131], v[162:163], v[130:131]
	v_mov_b32_e32 v150, v25
	v_mov_b32_e32 v151, v5
	v_mov_b32_dpp v154, v0 row_ror:1 row_mask:0xf bank_mask:0xf
	v_mov_b32_dpp v155, v199 row_ror:1 row_mask:0xf bank_mask:0xf
	v_mov_b32_dpp v0, v25 row_ror:15 row_mask:0xf bank_mask:0xf
	v_mov_b32_dpp v149, v5 row_ror:15 row_mask:0xf bank_mask:0xf
	v_mul_f32_e32 v148, 0xbfb8aa3b, v131
	v_pk_mul_f32 v[150:151], v[150:151], v[160:161]
	v_exp_f32_e32 v152, v148
	v_cndmask_b32_e64 v149, v149, v194, s[42:43]
	v_cndmask_b32_e64 v148, v0, v195, s[42:43]
	v_pk_fma_f32 v[150:151], v[164:165], v[154:155], v[150:151]
	v_mul_f32_e32 v133, v133, v159
	v_pk_fma_f32 v[148:149], v[148:149], v[156:157], v[150:151]
	v_add_f32_e32 v150, 1.0, v152
	v_pk_add_f32 v[148:149], v[162:163], v[148:149]
	v_rcp_f32_e32 v150, v150
	v_mul_f32_e32 v0, 0xbfb8aa3b, v149
	v_exp_f32_e32 v0, v0
	v_mul_f32_e32 v151, v132, v133
	v_mul_f32_e32 v131, v131, v150
	v_mul_f32_e32 v150, v130, v131
	v_add_f32_e32 v0, 1.0, v0
	v_rcp_f32_e32 v0, v0
	s_nop 0
	v_mul_f32_e32 v0, v149, v0
	v_mul_f32_e32 v148, v148, v0
	v_add_u32_e32 v0, v191, v192
	v_lshl_add_u64 v[132:133], v[0:1], 1, s[50:51]
	v_add_u32_e32 v0, v191, v193
	v_cvt_pk_bf16_f32 v130, v179, v169
	v_cvt_pk_bf16_f32 v131, v174, v158
	global_store_dwordx2 v[132:133], v[130:131], off
	v_lshl_add_u64 v[132:133], v[0:1], 1, s[50:51]
	v_add_u32_e32 v0, v191, v200
	v_cvt_pk_bf16_f32 v130, v180, v170
	v_cvt_pk_bf16_f32 v131, v175, v151
	global_store_dwordx2 v[132:133], v[130:131], off
	v_lshl_add_u64 v[132:133], v[0:1], 1, s[50:51]
	v_add_u32_e32 v0, v191, v190
	v_cvt_pk_bf16_f32 v130, v196, v171
	v_cvt_pk_bf16_f32 v131, v172, v150
	global_store_dwordx2 v[132:133], v[130:131], off
	v_lshl_add_u64 v[132:133], v[0:1], 1, s[50:51]
	v_cvt_pk_bf16_f32 v130, v198, v173
	v_cvt_pk_bf16_f32 v131, v168, v148
	global_store_dwordx2 v[132:133], v[130:131], off
	s_mov_b64 s[20:21], 0

; DI unsigned pk_bf16(float lo, float hi) { unsigned r; asm("v_cvt_pk_bf16_f32 %0, %1, %2" : "=v"(r) : "v"(lo), "v"(hi)); return r; }
;     DI void operator()(const f32x4 (&acc)[2][2][4][2], const Unit& u, int wr, int wc, int fr, int fq, LAS unsigned char* lds) const {
;     ...
;         if (mode == 0) {
;             bf16_t* Ob = (bf16_t*)out + (size_t)u.pm * BM * ldc + u.pn * BM;
; #pragma unroll
;             for (int ai = 0; ai < 2; ++ai)
; #pragma unroll
;                 for (int m = 0; m < 4; ++m)
; #pragma unroll
;                     for (int bj = 0; bj < 2; ++bj) { const int col = col0 + bj * HALF;
;                         const f32x4 v0 = acc[ai][bj][m][0], v1 = acc[ai][bj][m][1];
;                         u32x4 o; o[0] = pk_bf16(v0[0], v0[1]); o[1] = pk_bf16(v0[2], v0[3]); o[2] = pk_bf16(v1[0], v1[1]); o[3] = pk_bf16(v1[2], v1[3]);
;                         if (col < ncols) *(u32x4*)(Ob + ((rl0 + ai * HALF + m * 16) * (unsigned)IN_DIM + cl0 + bj * HALF)) = o; }
.LBB0_331:
	s_andn2_b64 vcc, exec, s[20:21]
	s_cbranch_vccnz .LBB0_233
	s_cmp_eq_u32 s29, 1
	s_mov_b64 s[18:19], -1
	s_cbranch_scc1 .LBB0_366
	s_add_i32 s11, s11, s48
	s_mul_i32 s18, s10, 0x264000
	v_or_b32_e32 v149, s11, v188
	s_mul_hi_i32 s11, s10, 0x264000
	s_add_u32 s20, s16, s18
	s_addc_u32 s11, s17, s11
	s_ashr_i32 s49, s48, 31
	s_lshl_b64 s[18:19], s[48:49], 1
	s_add_u32 s18, s20, s18
	s_addc_u32 s19, s11, s19
	s_movk_i32 s11, 0x1320
	v_mul_lo_u32 v148, v187, s11
	v_add_u32_e32 v0, v146, v148
	v_cmp_gt_i32_e32 vcc, s11, v149
	v_cvt_pk_bf16_f32 v130, v126, v127
	v_cvt_pk_bf16_f32 v131, v128, v129
	v_cvt_pk_bf16_f32 v132, v122, v123
	v_cvt_pk_bf16_f32 v133, v124, v125
	s_and_saveexec_b64 s[20:21], vcc
	s_cbranch_execz .LBB0_335
	v_lshl_add_u64 v[150:151], v[0:1], 1, s[18:19]
	global_store_dwordx4 v[150:151], v[130:133], off
.LBB0_335:
	s_or_b64 exec, exec, s[20:21]
	s_movk_i32 s11, 0x12a0
	v_cmp_gt_i32_e64 s[42:43], s11, v149
	v_cvt_pk_bf16_f32 v130, v110, v111
	v_cvt_pk_bf16_f32 v131, v112, v113
	v_cvt_pk_bf16_f32 v132, v102, v103
	v_cvt_pk_bf16_f32 v133, v104, v105
	s_and_saveexec_b64 s[20:21], s[42:43]
	s_cbranch_execz .LBB0_337
	v_add_u32_e32 v0, 0x80, v0
	v_lshl_add_u64 v[150:151], v[0:1], 1, s[18:19]
	global_store_dwordx4 v[150:151], v[130:133], off
.LBB0_337:
	s_or_b64 exec, exec, s[20:21]
	s_mov_b32 s11, 0x13200
	v_add3_u32 v0, v148, v146, s11
	v_cvt_pk_bf16_f32 v130, v118, v119
	v_cvt_pk_bf16_f32 v131, v120, v121
	v_cvt_pk_bf16_f32 v132, v114, v115
	v_cvt_pk_bf16_f32 v133, v116, v117
	s_and_saveexec_b64 s[20:21], vcc
	s_cbranch_execz .LBB0_339
	v_lshl_add_u64 v[150:151], v[0:1], 1, s[18:19]
	global_store_dwordx4 v[150:151], v[130:133], off
.LBB0_339:
	s_or_b64 exec, exec, s[20:21]
	s_nop 0
	v_cvt_pk_bf16_f32 v130, v94, v95
	v_cvt_pk_bf16_f32 v131, v96, v97
	v_cvt_pk_bf16_f32 v132, v86, v87
	v_cvt_pk_bf16_f32 v133, v88, v89
	s_and_saveexec_b64 s[20:21], s[42:43]
	s_cbranch_execz .LBB0_341
	v_add_u32_e32 v0, 0x80, v0
	v_lshl_add_u64 v[150:151], v[0:1], 1, s[18:19]
	global_store_dwordx4 v[150:151], v[130:133], off
.LBB0_341:
	s_or_b64 exec, exec, s[20:21]
	s_mov_b32 s11, 0x26400
	v_add3_u32 v0, v148, v146, s11
	v_cvt_pk_bf16_f32 v130, v106, v107
	v_cvt_pk_bf16_f32 v131, v108, v109
	v_cvt_pk_bf16_f32 v132, v98, v99
	v_cvt_pk_bf16_f32 v133, v100, v101
	s_and_saveexec_b64 s[20:21], vcc
	s_cbranch_execz .LBB0_343
	v_lshl_add_u64 v[150:151], v[0:1], 1, s[18:19]
	global_store_dwordx4 v[150:151], v[130:133], off
.LBB0_343:
	s_or_b64 exec, exec, s[20:21]
	s_nop 0
	v_cvt_pk_bf16_f32 v130, v78, v79
	v_cvt_pk_bf16_f32 v131, v80, v81
	v_cvt_pk_bf16_f32 v132, v74, v75
	v_cvt_pk_bf16_f32 v133, v76, v77
	s_and_saveexec_b64 s[20:21], s[42:43]
	s_cbranch_execz .LBB0_345
	v_add_u32_e32 v0, 0x80, v0
	v_lshl_add_u64 v[150:151], v[0:1], 1, s[18:19]
	global_store_dwordx4 v[150:151], v[130:133], off
.LBB0_345:
	s_or_b64 exec, exec, s[20:21]
	s_mov_b32 s11, 0x39600
	v_add3_u32 v0, v148, v146, s11
	v_cvt_pk_bf16_f32 v130, v90, v91
	v_cvt_pk_bf16_f32 v131, v92, v93
	v_cvt_pk_bf16_f32 v132, v82, v83
	v_cvt_pk_bf16_f32 v133, v84, v85
	s_and_saveexec_b64 s[20:21], vcc
	s_cbranch_execz .LBB0_347
	v_lshl_add_u64 v[150:151], v[0:1], 1, s[18:19]
	global_store_dwordx4 v[150:151], v[130:133], off
.LBB0_347:
	s_or_b64 exec, exec, s[20:21]
	s_nop 0
	v_cvt_pk_bf16_f32 v130, v70, v71
	v_cvt_pk_bf16_f32 v131, v72, v73
	v_cvt_pk_bf16_f32 v132, v66, v67
	v_cvt_pk_bf16_f32 v133, v68, v69
	s_and_saveexec_b64 s[20:21], s[42:43]
	s_cbranch_execz .LBB0_349
	v_add_u32_e32 v0, 0x80, v0
	v_lshl_add_u64 v[150:151], v[0:1], 1, s[18:19]
	global_store_dwordx4 v[150:151], v[130:133], off
.LBB0_349:
	s_or_b64 exec, exec, s[20:21]
	s_mov_b32 s11, 0x99000
	v_add3_u32 v0, v148, v146, s11
	v_cvt_pk_bf16_f32 v130, v62, v63
	v_cvt_pk_bf16_f32 v131, v64, v65
	v_cvt_pk_bf16_f32 v132, v58, v59
	v_cvt_pk_bf16_f32 v133, v60, v61
	s_and_saveexec_b64 s[20:21], vcc
	s_cbranch_execz .LBB0_351
	v_lshl_add_u64 v[150:151], v[0:1], 1, s[18:19]
	global_store_dwordx4 v[150:151], v[130:133], off
.LBB0_351:
	s_or_b64 exec, exec, s[20:21]
	s_nop 0
	v_cvt_pk_bf16_f32 v130, v42, v43
	v_cvt_pk_bf16_f32 v131, v44, v45
	v_cvt_pk_bf16_f32 v132, v34, v35
	v_cvt_pk_bf16_f32 v133, v36, v37
	s_and_saveexec_b64 s[20:21], s[42:43]
	s_cbranch_execz .LBB0_353
	v_add_u32_e32 v0, 0x80, v0
	v_lshl_add_u64 v[150:151], v[0:1], 1, s[18:19]
	global_store_dwordx4 v[150:151], v[130:133], off
.LBB0_353:
	s_or_b64 exec, exec, s[20:21]
	s_mov_b32 s11, 0xac200
	v_add3_u32 v0, v148, v146, s11
	v_cvt_pk_bf16_f32 v130, v54, v55
	v_cvt_pk_bf16_f32 v131, v56, v57
	v_cvt_pk_bf16_f32 v132, v50, v51
	v_cvt_pk_bf16_f32 v133, v52, v53
	s_and_saveexec_b64 s[20:21], vcc
	s_cbranch_execz .LBB0_355
	v_lshl_add_u64 v[150:151], v[0:1], 1, s[18:19]
	global_store_dwordx4 v[150:151], v[130:133], off
.LBB0_355:
	s_or_b64 exec, exec, s[20:21]
	s_nop 0
	v_cvt_pk_bf16_f32 v130, v26, v27
	v_cvt_pk_bf16_f32 v131, v28, v29
	v_cvt_pk_bf16_f32 v132, v18, v19
	v_cvt_pk_bf16_f32 v133, v20, v21
	s_and_saveexec_b64 s[20:21], s[42:43]
	s_cbranch_execz .LBB0_357
	v_add_u32_e32 v0, 0x80, v0
	v_lshl_add_u64 v[150:151], v[0:1], 1, s[18:19]
	global_store_dwordx4 v[150:151], v[130:133], off
.LBB0_357:
	s_or_b64 exec, exec, s[20:21]
	s_mov_b32 s11, 0xbf400
	v_add3_u32 v0, v148, v146, s11
	v_cvt_pk_bf16_f32 v130, v46, v47
	v_cvt_pk_bf16_f32 v131, v48, v49
	v_cvt_pk_bf16_f32 v132, v38, v39
	v_cvt_pk_bf16_f32 v133, v40, v41
	s_and_saveexec_b64 s[20:21], vcc
	s_cbranch_execz .LBB0_359
	v_lshl_add_u64 v[150:151], v[0:1], 1, s[18:19]
	global_store_dwordx4 v[150:151], v[130:133], off
.LBB0_359:
	s_or_b64 exec, exec, s[20:21]
	s_nop 0
	v_cvt_pk_bf16_f32 v130, v14, v15
	v_cvt_pk_bf16_f32 v131, v16, v17
	v_cvt_pk_bf16_f32 v132, v10, v11
	v_cvt_pk_bf16_f32 v133, v12, v13
	s_and_saveexec_b64 s[20:21], s[42:43]
	s_cbranch_execz .LBB0_361
	v_add_u32_e32 v0, 0x80, v0
	v_lshl_add_u64 v[150:151], v[0:1], 1, s[18:19]
	global_store_dwordx4 v[150:151], v[130:133], off
.LBB0_361:
	s_or_b64 exec, exec, s[20:21]
	s_mov_b32 s11, 0xd2600
	v_add3_u32 v0, v148, v146, s11
	v_cvt_pk_bf16_f32 v130, v30, v31
	v_cvt_pk_bf16_f32 v131, v32, v33
	v_cvt_pk_bf16_f32 v132, v22, v23
	v_cvt_pk_bf16_f32 v133, v24, v25
	s_and_saveexec_b64 s[20:21], vcc
	s_cbranch_execz .LBB0_363
	v_lshl_add_u64 v[148:149], v[0:1], 1, s[18:19]
	global_store_dwordx4 v[148:149], v[130:133], off
.LBB0_363:
	s_or_b64 exec, exec, s[20:21]
	s_nop 0
	v_cvt_pk_bf16_f32 v130, v6, v7
	v_cvt_pk_bf16_f32 v131, v8, v9
	v_cvt_pk_bf16_f32 v132, v2, v3
	v_cvt_pk_bf16_f32 v133, v4, v5
	s_and_saveexec_b64 s[20:21], s[42:43]
	s_cbranch_execz .LBB0_365
	v_add_u32_e32 v0, 0x80, v0
	v_lshl_add_u64 v[148:149], v[0:1], 1, s[18:19]
	global_store_dwordx4 v[148:149], v[130:133], off

;     DI void operator()(const f32x4 (&acc)[2][2][4][2], const Unit& u, int wr, int wc, int fr, int fq, LAS unsigned char* lds) const {
;     ...
;             float* Cb = (float*)out + (size_t)u.pm * BM * 1024 + u.pn * BM;
; #pragma unroll
;             for (int ai = 0; ai < 2; ++ai)
; #pragma unroll
;                 for (int m = 0; m < 4; ++m)
; #pragma unroll
;                     for (int bj = 0; bj < 2; ++bj) { float* rp = Cb + ((rl0 + ai * HALF + m * 16) * 1024u + cl0 + bj * HALF);
;                         *(f32x4*)rp = acc[ai][bj][m][0]; *(f32x4*)(rp + 4) = acc[ai][bj][m][1]; }
.LBB0_366:
	s_and_b64 vcc, exec, s[18:19]
	s_cbranch_vccz .LBB0_233
	s_ashr_i32 s11, s10, 31
	s_lshl_b64 s[10:11], s[10:11], 20
	s_add_u32 s16, s16, s10
	s_addc_u32 s17, s17, s11
	s_ashr_i32 s49, s48, 31
	s_lshl_b64 s[10:11], s[48:49], 2
	s_add_u32 s10, s16, s10
	s_addc_u32 s11, s17, s11
	v_lshl_add_u32 v0, v187, 10, v146
	v_lshl_add_u64 v[130:131], v[0:1], 2, s[10:11]
	global_store_dwordx4 v[130:131], v[126:129], off
	global_store_dwordx4 v[130:131], v[122:125], off offset:16
	s_nop 1
	v_add_u32_e32 v122, 0x80, v0
	v_mov_b32_e32 v123, v1
	v_lshl_add_u64 v[122:123], v[122:123], 2, s[10:11]
	global_store_dwordx4 v[122:123], v[110:113], off
	global_store_dwordx4 v[122:123], v[102:105], off offset:16
	s_nop 1
	v_add_u32_e32 v102, 0x4000, v0
	v_mov_b32_e32 v103, v1
	v_lshl_add_u64 v[102:103], v[102:103], 2, s[10:11]
	global_store_dwordx4 v[102:103], v[118:121], off
	global_store_dwordx4 v[102:103], v[114:117], off offset:16
	v_add_u32_e32 v102, 0x4080, v0
	v_mov_b32_e32 v103, v1
	v_lshl_add_u64 v[102:103], v[102:103], 2, s[10:11]
	global_store_dwordx4 v[102:103], v[94:97], off
	global_store_dwordx4 v[102:103], v[86:89], off offset:16
	s_nop 1
	v_add_u32_e32 v86, 0x8000, v0
	v_mov_b32_e32 v87, v1
	v_lshl_add_u64 v[86:87], v[86:87], 2, s[10:11]
	global_store_dwordx4 v[86:87], v[106:109], off
	global_store_dwordx4 v[86:87], v[98:101], off offset:16
	v_add_u32_e32 v86, 0x8080, v0
	v_mov_b32_e32 v87, v1
	v_lshl_add_u64 v[86:87], v[86:87], 2, s[10:11]
	global_store_dwordx4 v[86:87], v[78:81], off
	global_store_dwordx4 v[86:87], v[74:77], off offset:16
	s_nop 1
	v_add_u32_e32 v74, 0xc000, v0
	v_mov_b32_e32 v75, v1
	v_lshl_add_u64 v[74:75], v[74:75], 2, s[10:11]
	global_store_dwordx4 v[74:75], v[90:93], off
	global_store_dwordx4 v[74:75], v[82:85], off offset:16
	v_add_u32_e32 v74, 0xc080, v0
	v_mov_b32_e32 v75, v1
	v_lshl_add_u64 v[74:75], v[74:75], 2, s[10:11]
	global_store_dwordx4 v[74:75], v[70:73], off
	global_store_dwordx4 v[74:75], v[66:69], off offset:16
	s_nop 1
	v_add_u32_e32 v66, 0x20000, v0
	v_mov_b32_e32 v67, v1
	v_lshl_add_u64 v[66:67], v[66:67], 2, s[10:11]
	global_store_dwordx4 v[66:67], v[62:65], off
	global_store_dwordx4 v[66:67], v[58:61], off offset:16
	s_nop 1
	v_add_u32_e32 v58, 0x20080, v0
	v_mov_b32_e32 v59, v1
	v_lshl_add_u64 v[58:59], v[58:59], 2, s[10:11]
	global_store_dwordx4 v[58:59], v[42:45], off
	global_store_dwordx4 v[58:59], v[34:37], off offset:16
	s_nop 1
	v_add_u32_e32 v34, 0x24000, v0
	v_mov_b32_e32 v35, v1
	v_lshl_add_u64 v[34:35], v[34:35], 2, s[10:11]
	global_store_dwordx4 v[34:35], v[54:57], off
	global_store_dwordx4 v[34:35], v[50:53], off offset:16
	v_add_u32_e32 v34, 0x24080, v0
	v_mov_b32_e32 v35, v1
	v_lshl_add_u64 v[34:35], v[34:35], 2, s[10:11]
	global_store_dwordx4 v[34:35], v[26:29], off
	global_store_dwordx4 v[34:35], v[18:21], off offset:16
	s_nop 1
	v_add_u32_e32 v18, 0x28000, v0
	v_mov_b32_e32 v19, v1
	v_lshl_add_u64 v[18:19], v[18:19], 2, s[10:11]
	global_store_dwordx4 v[18:19], v[46:49], off
	global_store_dwordx4 v[18:19], v[38:41], off offset:16
	v_add_u32_e32 v18, 0x28080, v0
	v_mov_b32_e32 v19, v1
	v_lshl_add_u64 v[18:19], v[18:19], 2, s[10:11]
	global_store_dwordx4 v[18:19], v[14:17], off
	global_store_dwordx4 v[18:19], v[10:13], off offset:16
	s_nop 1
	v_add_u32_e32 v10, 0x2c000, v0
	v_mov_b32_e32 v11, v1
	v_lshl_add_u64 v[10:11], v[10:11], 2, s[10:11]
	v_add_u32_e32 v0, 0x2c080, v0
	global_store_dwordx4 v[10:11], v[30:33], off
	global_store_dwordx4 v[10:11], v[22:25], off offset:16
	v_lshl_add_u64 v[10:11], v[0:1], 2, s[10:11]
	global_store_dwordx4 v[10:11], v[6:9], off
	global_store_dwordx4 v[10:11], v[2:5], off offset:16
	s_branch .LBB0_233
